# peeled first K-loop trip (inline-zero SrcC, no accumulator zeroing) in six GEMM phases + r1 row-scale loads hoisted in w_in epilogue + EpiRes rewrite
# speedup vs baseline: 1.0231x; 1.0231x over previous
.LBB0_141:
	s_lshl_b32 s34, s11, 8
	s_ashr_i32 s35, s34, 31
	s_lshl_b64 s[34:35], s[34:35], 11
	s_add_u32 s82, s49, s34
	s_addc_u32 s83, s53, s35
	s_and_b64 s[34:35], s[0:1], exec
	s_cselect_b32 s5, s83, s7
	s_cselect_b32 s22, s82, s6
	s_ashr_i32 s81, s80, 31
	s_lshl_b64 s[34:35], s[80:81], 19
	s_add_u32 s84, s55, s34
	s_addc_u32 s85, s57, s35
	s_and_b64 s[34:35], s[0:1], exec
	s_cselect_b32 s34, s85, s9
	s_cselect_b32 s35, s84, s8
	s_add_u32 s40, s8, 0x100
	s_addc_u32 s41, s9, 0
	s_mov_b32 s50, -2
	s_waitcnt vmcnt(0)
	s_waitcnt lgkmcnt(0)
	ds_read_b128 v[128:131], v175
	ds_read_b128 v[132:135], v175 offset:1024
	ds_read_b128 v[136:139], v175 offset:2048
	ds_read_b128 v[140:143], v175 offset:3072
	ds_read_b128 v[166:169], v176
	ds_read_b128 v[170:173], v176 offset:1024
	ds_read_b128 v[182:185], v176 offset:2048
	ds_read_b128 v[186:189], v176 offset:3072
	s_add_u32 s8, s6, 0x100
	s_addc_u32 s9, s7, 0
	s_cmp_eq_u32 s50, 12
	s_cselect_b32 s89, s5, s9
	s_cselect_b32 s88, s22, s8
	s_cselect_b32 s87, s34, s41
	s_cselect_b32 s86, s35, s40
	v_lshl_add_u64 v[220:221], s[6:7], 0, v[158:159]
	s_add_i32 m0, s61, 0xc000
	ds_read_b128 v[190:193], v177
	ds_read_b128 v[194:197], v177 offset:1024
	ds_read_b128 v[198:201], v177 offset:2048
	ds_read_b128 v[202:205], v177 offset:3072
	ds_read_b128 v[206:209], v177 offset:4096
	ds_read_b128 v[210:213], v177 offset:5120
	ds_read_b128 v[214:217], v177 offset:6144
	ds_read_b128 v[224:227], v177 offset:7168
	global_load_lds_dwordx4 v[220:221], off
	v_lshl_add_u64 v[220:221], s[6:7], 0, v[160:161]
	s_add_i32 m0, s61, 0xe000
	s_nop 0
	global_load_lds_dwordx4 v[220:221], off
	s_waitcnt vmcnt(8)
	s_waitcnt lgkmcnt(0)
	s_barrier
	s_setprio 1
	s_waitcnt lgkmcnt(0)
	v_mfma_f32_16x16x32_bf16 v[124:127], v[128:131], v[190:193], 0
	v_mfma_f32_16x16x32_bf16 v[120:123], v[136:139], v[190:193], 0
	v_mfma_f32_16x16x32_bf16 v[108:111], v[128:131], v[198:201], 0
	v_mfma_f32_16x16x32_bf16 v[104:107], v[136:139], v[198:201], 0
	v_mfma_f32_16x16x32_bf16 v[92:95], v[128:131], v[206:209], 0
	v_mfma_f32_16x16x32_bf16 v[88:91], v[136:139], v[206:209], 0
	v_mfma_f32_16x16x32_bf16 v[76:79], v[128:131], v[214:217], 0
	v_mfma_f32_16x16x32_bf16 v[72:75], v[136:139], v[214:217], 0
	v_mfma_f32_16x16x32_bf16 v[124:127], v[132:135], v[194:197], v[124:127]
	v_mfma_f32_16x16x32_bf16 v[120:123], v[140:143], v[194:197], v[120:123]
	v_mfma_f32_16x16x32_bf16 v[108:111], v[132:135], v[202:205], v[108:111]
	v_mfma_f32_16x16x32_bf16 v[104:107], v[140:143], v[202:205], v[104:107]
	v_mfma_f32_16x16x32_bf16 v[92:95], v[132:135], v[210:213], v[92:95]
	v_mfma_f32_16x16x32_bf16 v[88:91], v[140:143], v[210:213], v[88:91]
	v_mfma_f32_16x16x32_bf16 v[76:79], v[132:135], v[224:227], v[76:79]
	v_mfma_f32_16x16x32_bf16 v[72:75], v[140:143], v[224:227], v[72:75]
	s_setprio 0
	s_setprio 1
	v_mfma_f32_16x16x32_bf16 v[116:119], v[166:169], v[190:193], 0
	v_mfma_f32_16x16x32_bf16 v[112:115], v[182:185], v[190:193], 0
	v_mfma_f32_16x16x32_bf16 v[100:103], v[166:169], v[198:201], 0
	v_mfma_f32_16x16x32_bf16 v[96:99], v[182:185], v[198:201], 0
	v_mfma_f32_16x16x32_bf16 v[84:87], v[166:169], v[206:209], 0
	v_mfma_f32_16x16x32_bf16 v[80:83], v[182:185], v[206:209], 0
	v_mfma_f32_16x16x32_bf16 v[68:71], v[166:169], v[214:217], 0
	v_mfma_f32_16x16x32_bf16 v[64:67], v[182:185], v[214:217], 0
	v_mfma_f32_16x16x32_bf16 v[116:119], v[170:173], v[194:197], v[116:119]
	v_mfma_f32_16x16x32_bf16 v[112:115], v[186:189], v[194:197], v[112:115]
	v_mfma_f32_16x16x32_bf16 v[100:103], v[170:173], v[202:205], v[100:103]
	v_mfma_f32_16x16x32_bf16 v[96:99], v[186:189], v[202:205], v[96:99]
	v_mfma_f32_16x16x32_bf16 v[84:87], v[170:173], v[210:213], v[84:87]
	v_mfma_f32_16x16x32_bf16 v[80:83], v[186:189], v[210:213], v[80:83]
	v_mfma_f32_16x16x32_bf16 v[68:71], v[170:173], v[224:227], v[68:71]
	v_mfma_f32_16x16x32_bf16 v[64:67], v[186:189], v[224:227], v[64:67]
	s_setprio 0
	s_barrier
	s_add_i32 s6, s37, s59
	v_lshl_add_u64 v[220:221], s[86:87], 0, v[148:149]
	s_mov_b32 m0, s6
	ds_read_b128 v[190:193], v177 offset:16384
	ds_read_b128 v[194:197], v177 offset:17408
	ds_read_b128 v[198:201], v177 offset:18432
	ds_read_b128 v[202:205], v177 offset:19456
	ds_read_b128 v[206:209], v177 offset:20480
	ds_read_b128 v[210:213], v177 offset:21504
	ds_read_b128 v[214:217], v177 offset:22528
	ds_read_b128 v[224:227], v177 offset:23552
	global_load_lds_dwordx4 v[220:221], off
	s_add_i32 m0, s6, 0x2000
	s_add_u32 s6, s86, 0x40000
	v_lshl_add_u64 v[228:229], s[86:87], 0, v[152:153]
	s_addc_u32 s7, s87, 0
	s_add_i32 s51, s97, s59
	global_load_lds_dwordx4 v[228:229], off
	v_lshl_add_u64 v[230:231], s[6:7], 0, v[148:149]
	s_mov_b32 m0, s51
	v_lshl_add_u64 v[232:233], s[88:89], 0, v[150:151]
	global_load_lds_dwordx4 v[230:231], off
	v_lshl_add_u64 v[230:231], s[6:7], 0, v[152:153]
	s_add_i32 m0, s51, 0x2000
	v_lshl_add_u64 v[234:235], v[232:233], 0, s[68:69]
	global_load_lds_dwordx4 v[230:231], off
	v_lshl_add_u64 v[230:231], s[88:89], 0, v[146:147]
	s_mov_b32 m0, s61
	s_nop 0
	global_load_lds_dwordx4 v[230:231], off
	s_mov_b32 m0, s63
	s_nop 0
	global_load_lds_dwordx4 v[234:235], off
	s_waitcnt vmcnt(8)
	s_waitcnt lgkmcnt(0)
	s_barrier
	s_setprio 1
	s_waitcnt lgkmcnt(0)
	v_mfma_f32_16x16x32_bf16 v[60:63], v[128:131], v[190:193], 0
	v_mfma_f32_16x16x32_bf16 v[56:59], v[136:139], v[190:193], 0
	v_mfma_f32_16x16x32_bf16 v[44:47], v[128:131], v[198:201], 0
	v_mfma_f32_16x16x32_bf16 v[40:43], v[136:139], v[198:201], 0
	v_mfma_f32_16x16x32_bf16 v[28:31], v[128:131], v[206:209], 0
	v_mfma_f32_16x16x32_bf16 v[24:27], v[136:139], v[206:209], 0
	v_mfma_f32_16x16x32_bf16 v[12:15], v[128:131], v[214:217], 0
	v_mfma_f32_16x16x32_bf16 v[8:11], v[136:139], v[214:217], 0
	v_mfma_f32_16x16x32_bf16 v[60:63], v[132:135], v[194:197], v[60:63]
	v_mfma_f32_16x16x32_bf16 v[56:59], v[140:143], v[194:197], v[56:59]
	v_mfma_f32_16x16x32_bf16 v[44:47], v[132:135], v[202:205], v[44:47]
	v_mfma_f32_16x16x32_bf16 v[40:43], v[140:143], v[202:205], v[40:43]
	v_mfma_f32_16x16x32_bf16 v[28:31], v[132:135], v[210:213], v[28:31]
	v_mfma_f32_16x16x32_bf16 v[24:27], v[140:143], v[210:213], v[24:27]
	v_mfma_f32_16x16x32_bf16 v[12:15], v[132:135], v[224:227], v[12:15]
	v_mfma_f32_16x16x32_bf16 v[8:11], v[140:143], v[224:227], v[8:11]
	s_setprio 0
	s_setprio 1
	v_mfma_f32_16x16x32_bf16 v[52:55], v[166:169], v[190:193], 0
	v_mfma_f32_16x16x32_bf16 v[48:51], v[182:185], v[190:193], 0
	v_mfma_f32_16x16x32_bf16 v[36:39], v[166:169], v[198:201], 0
	v_mfma_f32_16x16x32_bf16 v[32:35], v[182:185], v[198:201], 0
	v_mfma_f32_16x16x32_bf16 v[20:23], v[166:169], v[206:209], 0
	v_mfma_f32_16x16x32_bf16 v[16:19], v[182:185], v[206:209], 0
	v_mfma_f32_16x16x32_bf16 v[4:7], v[166:169], v[214:217], 0
	v_mfma_f32_16x16x32_bf16 v[0:3], v[182:185], v[214:217], 0
	v_mfma_f32_16x16x32_bf16 v[52:55], v[170:173], v[194:197], v[52:55]
	v_mfma_f32_16x16x32_bf16 v[48:51], v[186:189], v[194:197], v[48:51]
	v_mfma_f32_16x16x32_bf16 v[36:39], v[170:173], v[202:205], v[36:39]
	v_mfma_f32_16x16x32_bf16 v[32:35], v[186:189], v[202:205], v[32:35]
	v_mfma_f32_16x16x32_bf16 v[20:23], v[170:173], v[210:213], v[20:23]
	v_mfma_f32_16x16x32_bf16 v[16:19], v[186:189], v[210:213], v[16:19]
	v_mfma_f32_16x16x32_bf16 v[4:7], v[170:173], v[224:227], v[4:7]
	v_mfma_f32_16x16x32_bf16 v[0:3], v[186:189], v[224:227], v[0:3]
	s_setprio 0
	s_barrier
	s_add_i32 s6, 0, 0x18000
	s_add_i32 s51, 0, 0x1c000
	v_add_u32_e32 v140, s6, v174
	v_add_u32_e32 v154, s51, v174
	ds_read_b128 v[128:131], v140
	ds_read_b128 v[132:135], v140 offset:1024
	ds_read_b128 v[136:139], v140 offset:2048
	ds_read_b128 v[140:143], v140 offset:3072
	ds_read_b128 v[166:169], v154
	ds_read_b128 v[170:173], v154 offset:1024
	ds_read_b128 v[182:185], v154 offset:2048
	ds_read_b128 v[186:189], v154 offset:3072
	s_mov_b32 m0, s65
	v_lshl_add_u64 v[234:235], v[230:231], 0, s[66:67]
	ds_read_b128 v[190:193], v177 offset:32768
	ds_read_b128 v[194:197], v177 offset:33792
	ds_read_b128 v[198:201], v177 offset:34816
	ds_read_b128 v[202:205], v177 offset:35840
	ds_read_b128 v[206:209], v177 offset:36864
	ds_read_b128 v[210:213], v177 offset:37888
	ds_read_b128 v[214:217], v177 offset:38912
	ds_read_b128 v[224:227], v177 offset:39936
	global_load_lds_dwordx4 v[234:235], off
	v_lshl_add_u64 v[234:235], v[232:233], 0, s[46:47]
	s_mov_b32 m0, s77
	s_nop 0
	global_load_lds_dwordx4 v[234:235], off
	s_waitcnt vmcnt(8)
	s_waitcnt lgkmcnt(0)
	s_barrier
	s_setprio 1
	s_waitcnt lgkmcnt(0)
	v_mfma_f32_16x16x32_bf16 v[124:127], v[128:131], v[190:193], v[124:127]
	v_mfma_f32_16x16x32_bf16 v[120:123], v[136:139], v[190:193], v[120:123]
	v_mfma_f32_16x16x32_bf16 v[108:111], v[128:131], v[198:201], v[108:111]
	v_mfma_f32_16x16x32_bf16 v[104:107], v[136:139], v[198:201], v[104:107]
	v_mfma_f32_16x16x32_bf16 v[92:95], v[128:131], v[206:209], v[92:95]
	v_mfma_f32_16x16x32_bf16 v[88:91], v[136:139], v[206:209], v[88:91]
	v_mfma_f32_16x16x32_bf16 v[76:79], v[128:131], v[214:217], v[76:79]
	v_mfma_f32_16x16x32_bf16 v[72:75], v[136:139], v[214:217], v[72:75]
	v_mfma_f32_16x16x32_bf16 v[124:127], v[132:135], v[194:197], v[124:127]
	v_mfma_f32_16x16x32_bf16 v[120:123], v[140:143], v[194:197], v[120:123]
	v_mfma_f32_16x16x32_bf16 v[108:111], v[132:135], v[202:205], v[108:111]
	v_mfma_f32_16x16x32_bf16 v[104:107], v[140:143], v[202:205], v[104:107]
	v_mfma_f32_16x16x32_bf16 v[92:95], v[132:135], v[210:213], v[92:95]
	v_mfma_f32_16x16x32_bf16 v[88:91], v[140:143], v[210:213], v[88:91]
	v_mfma_f32_16x16x32_bf16 v[76:79], v[132:135], v[224:227], v[76:79]
	v_mfma_f32_16x16x32_bf16 v[72:75], v[140:143], v[224:227], v[72:75]
	s_setprio 0
	s_setprio 1
	v_mfma_f32_16x16x32_bf16 v[116:119], v[166:169], v[190:193], v[116:119]
	v_mfma_f32_16x16x32_bf16 v[112:115], v[182:185], v[190:193], v[112:115]
	v_mfma_f32_16x16x32_bf16 v[100:103], v[166:169], v[198:201], v[100:103]
	v_mfma_f32_16x16x32_bf16 v[96:99], v[182:185], v[198:201], v[96:99]
	v_mfma_f32_16x16x32_bf16 v[84:87], v[166:169], v[206:209], v[84:87]
	v_mfma_f32_16x16x32_bf16 v[80:83], v[182:185], v[206:209], v[80:83]
	v_mfma_f32_16x16x32_bf16 v[68:71], v[166:169], v[214:217], v[68:71]
	v_mfma_f32_16x16x32_bf16 v[64:67], v[182:185], v[214:217], v[64:67]
	v_mfma_f32_16x16x32_bf16 v[116:119], v[170:173], v[194:197], v[116:119]
	v_mfma_f32_16x16x32_bf16 v[112:115], v[186:189], v[194:197], v[112:115]
	v_mfma_f32_16x16x32_bf16 v[100:103], v[170:173], v[202:205], v[100:103]
	v_mfma_f32_16x16x32_bf16 v[96:99], v[186:189], v[202:205], v[96:99]
	v_mfma_f32_16x16x32_bf16 v[84:87], v[170:173], v[210:213], v[84:87]
	v_mfma_f32_16x16x32_bf16 v[80:83], v[186:189], v[210:213], v[80:83]
	v_mfma_f32_16x16x32_bf16 v[68:71], v[170:173], v[224:227], v[68:71]
	v_mfma_f32_16x16x32_bf16 v[64:67], v[186:189], v[224:227], v[64:67]
	s_setprio 0
	s_barrier
	s_add_i32 s6, s6, s59
	v_lshl_add_u64 v[220:221], v[220:221], 0, s[42:43]
	s_mov_b32 m0, s6
	ds_read_b128 v[190:193], v177 offset:49152
	ds_read_b128 v[194:197], v177 offset:50176
	ds_read_b128 v[198:201], v177 offset:51200
	ds_read_b128 v[202:205], v177 offset:52224
	ds_read_b128 v[206:209], v177 offset:53248
	ds_read_b128 v[210:213], v177 offset:54272
	ds_read_b128 v[214:217], v177 offset:55296
	ds_read_b128 v[224:227], v177 offset:56320
	global_load_lds_dwordx4 v[220:221], off
	s_add_i32 m0, s6, 0x2000
	s_add_u32 s6, s86, 0x40080
	v_lshl_add_u64 v[220:221], v[228:229], 0, s[42:43]
	s_addc_u32 s7, s87, 0
	s_add_i32 s51, s51, s59
	global_load_lds_dwordx4 v[220:221], off
	v_lshl_add_u64 v[220:221], s[6:7], 0, v[148:149]
	s_mov_b32 m0, s51
	s_nop 0
	global_load_lds_dwordx4 v[220:221], off
	v_lshl_add_u64 v[220:221], s[6:7], 0, v[152:153]
	s_add_i32 m0, s51, 0x2000
	s_nop 0
	global_load_lds_dwordx4 v[220:221], off
	v_lshl_add_u64 v[220:221], v[230:231], 0, s[42:43]
	s_mov_b32 m0, s91
	s_nop 0
	global_load_lds_dwordx4 v[220:221], off
	v_lshl_add_u64 v[220:221], v[232:233], 0, s[44:45]
	s_mov_b32 m0, s92
	s_nop 0
	global_load_lds_dwordx4 v[220:221], off
	s_waitcnt vmcnt(8)
	s_waitcnt lgkmcnt(0)
	s_barrier
	s_setprio 1
	s_waitcnt lgkmcnt(0)
	v_mfma_f32_16x16x32_bf16 v[60:63], v[128:131], v[190:193], v[60:63]
	v_mfma_f32_16x16x32_bf16 v[56:59], v[136:139], v[190:193], v[56:59]
	v_mfma_f32_16x16x32_bf16 v[44:47], v[128:131], v[198:201], v[44:47]
	v_mfma_f32_16x16x32_bf16 v[40:43], v[136:139], v[198:201], v[40:43]
	v_mfma_f32_16x16x32_bf16 v[28:31], v[128:131], v[206:209], v[28:31]
	v_mfma_f32_16x16x32_bf16 v[24:27], v[136:139], v[206:209], v[24:27]
	v_mfma_f32_16x16x32_bf16 v[12:15], v[128:131], v[214:217], v[12:15]
	v_mfma_f32_16x16x32_bf16 v[8:11], v[136:139], v[214:217], v[8:11]
	v_mfma_f32_16x16x32_bf16 v[60:63], v[132:135], v[194:197], v[60:63]
	v_mfma_f32_16x16x32_bf16 v[56:59], v[140:143], v[194:197], v[56:59]
	v_mfma_f32_16x16x32_bf16 v[44:47], v[132:135], v[202:205], v[44:47]
	v_mfma_f32_16x16x32_bf16 v[40:43], v[140:143], v[202:205], v[40:43]
	v_mfma_f32_16x16x32_bf16 v[28:31], v[132:135], v[210:213], v[28:31]
	v_mfma_f32_16x16x32_bf16 v[24:27], v[140:143], v[210:213], v[24:27]
	v_mfma_f32_16x16x32_bf16 v[12:15], v[132:135], v[224:227], v[12:15]
	v_mfma_f32_16x16x32_bf16 v[8:11], v[140:143], v[224:227], v[8:11]
	s_setprio 0
	s_setprio 1
	v_mfma_f32_16x16x32_bf16 v[52:55], v[166:169], v[190:193], v[52:55]
	v_mfma_f32_16x16x32_bf16 v[48:51], v[182:185], v[190:193], v[48:51]
	v_mfma_f32_16x16x32_bf16 v[36:39], v[166:169], v[198:201], v[36:39]
	v_mfma_f32_16x16x32_bf16 v[32:35], v[182:185], v[198:201], v[32:35]
	v_mfma_f32_16x16x32_bf16 v[20:23], v[166:169], v[206:209], v[20:23]
	v_mfma_f32_16x16x32_bf16 v[16:19], v[182:185], v[206:209], v[16:19]
	v_mfma_f32_16x16x32_bf16 v[4:7], v[166:169], v[214:217], v[4:7]
	v_mfma_f32_16x16x32_bf16 v[0:3], v[182:185], v[214:217], v[0:3]
	v_mfma_f32_16x16x32_bf16 v[52:55], v[170:173], v[194:197], v[52:55]
	v_mfma_f32_16x16x32_bf16 v[48:51], v[186:189], v[194:197], v[48:51]
	v_mfma_f32_16x16x32_bf16 v[36:39], v[170:173], v[202:205], v[36:39]
	v_mfma_f32_16x16x32_bf16 v[32:35], v[186:189], v[202:205], v[32:35]
	v_mfma_f32_16x16x32_bf16 v[20:23], v[170:173], v[210:213], v[20:23]
	v_mfma_f32_16x16x32_bf16 v[16:19], v[186:189], v[210:213], v[16:19]
	v_mfma_f32_16x16x32_bf16 v[4:7], v[170:173], v[224:227], v[4:7]
	v_mfma_f32_16x16x32_bf16 v[0:3], v[186:189], v[224:227], v[0:3]
	s_setprio 0
	s_barrier
	s_add_i32 s50, s50, 2
	s_add_u32 s40, s40, 0x100
	s_addc_u32 s41, s41, 0
	s_cmp_gt_u32 s50, 13
	s_mov_b64 s[6:7], s[8:9]

.LBB0_148:
	v_readlane_b32 s12, v249, 0
	v_readlane_b32 s26, v249, 14
	v_readlane_b32 s27, v249, 15
	s_cmp_eq_u32 s3, 3
	s_cselect_b64 s[6:7], -1, 0
	v_lshl_add_u64 v[128:129], v[166:167], 2, s[26:27]
	global_load_dword v130, v[128:129], off
	global_load_dword v237, v[128:129], off offset:64
	global_load_dword v238, v[128:129], off offset:128
	global_load_dword v239, v[128:129], off offset:192
	global_load_dword v240, v[128:129], off offset:512
	global_load_dword v241, v[128:129], off offset:576
	global_load_dword v242, v[128:129], off offset:640
	global_load_dword v243, v[128:129], off offset:704
	s_and_b32 s3, s4, -2
	s_cmp_lg_u32 s3, 2
	s_cselect_b64 s[88:89], -1, 0
	s_mov_b64 s[8:9], -1
	s_and_b64 vcc, exec, s[88:89]
	v_readlane_b32 s13, v249, 1
	v_readlane_b32 s14, v249, 2
	v_readlane_b32 s15, v249, 3
	v_readlane_b32 s16, v249, 4
	v_readlane_b32 s17, v249, 5
	v_readlane_b32 s18, v249, 6
	v_readlane_b32 s19, v249, 7
	v_readlane_b32 s20, v249, 8
	v_readlane_b32 s21, v249, 9
	v_readlane_b32 s22, v249, 10
	v_readlane_b32 s23, v249, 11
	v_readlane_b32 s24, v249, 12
	v_readlane_b32 s25, v249, 13
	s_waitcnt vmcnt(7)
	v_mul_f32_e32 v131, 0xbfb8aa3b, v130
	v_cndmask_b32_e64 v130, v130, v131, s[6:7]
	v_cndmask_b32_e64 v131, 0, 1, s[6:7]
	v_pk_mul_f32 v[140:141], v[126:127], v[130:131] op_sel_hi:[1,0]
	v_pk_mul_f32 v[142:143], v[124:125], v[130:131] op_sel_hi:[1,0]
	v_pk_mul_f32 v[132:133], v[122:123], v[130:131] op_sel_hi:[1,0]
	v_pk_mul_f32 v[134:135], v[120:121], v[130:131] op_sel_hi:[1,0]
	v_cmp_ne_u32_e64 s[4:5], 1, v131
	s_cbranch_vccz .LBB0_152
	s_and_b64 vcc, exec, s[4:5]
	v_mov_b32_e32 v171, v133
	v_mov_b32_e32 v170, v132
	v_mov_b32_e32 v169, v135
	v_mov_b32_e32 v168, v134
	v_mov_b32_e32 v137, v141
	v_mov_b32_e32 v136, v140
	v_mov_b32_e32 v139, v143
	v_mov_b32_e32 v138, v142
	s_cbranch_vccnz .LBB0_151
	v_exp_f32_e32 v131, v142
	v_exp_f32_e32 v136, v143
	v_exp_f32_e32 v137, v140
	v_exp_f32_e32 v154, v134
	v_add_f32_e32 v131, 1.0, v131
	v_rcp_f32_e32 v138, v131
	v_exp_f32_e32 v131, v141
	v_add_f32_e32 v136, 1.0, v136
	v_rcp_f32_e32 v139, v136
	v_add_f32_e32 v136, 1.0, v137
	v_add_f32_e32 v131, 1.0, v131
	v_rcp_f32_e32 v137, v131
	v_exp_f32_e32 v131, v135
	v_add_f32_e32 v154, 1.0, v154
	v_rcp_f32_e32 v168, v154
	v_exp_f32_e32 v154, v132
	v_exp_f32_e32 v171, v133
	v_add_f32_e32 v131, 1.0, v131
	v_rcp_f32_e32 v169, v131
	v_add_f32_e32 v131, 1.0, v154
	v_rcp_f32_e32 v170, v131
	v_add_f32_e32 v131, 1.0, v171
	v_rcp_f32_e32 v136, v136
	v_rcp_f32_e32 v171, v131

.LBB0_160:
	v_cvt_pk_bf16_f32 v134, v140, v141
	v_cvt_pk_bf16_f32 v135, v138, v139
	s_nop 0
	v_cvt_pk_bf16_f32 v136, v168, v169
	v_cvt_pk_bf16_f32 v137, v170, v171
	global_store_dwordx4 v[132:133], v[134:137], off offset:256
	s_waitcnt vmcnt(8)
	v_mov_b32_e32 v130, v237
	s_and_b64 vcc, exec, s[8:9]
	s_mov_b64 s[88:89], -1
	s_waitcnt vmcnt(8)
	v_mul_f32_e32 v131, 0xbfb8aa3b, v130
	v_cndmask_b32_e64 v130, v130, v131, s[6:7]
	v_pk_mul_f32 v[140:141], v[110:111], v[130:131] op_sel_hi:[1,0]
	v_pk_mul_f32 v[142:143], v[108:109], v[130:131] op_sel_hi:[1,0]
	v_pk_mul_f32 v[132:133], v[106:107], v[130:131] op_sel_hi:[1,0]
	v_pk_mul_f32 v[134:135], v[104:105], v[130:131] op_sel_hi:[1,0]
	s_cbranch_vccnz .LBB0_164
	s_and_b64 vcc, exec, s[4:5]
	v_mov_b32_e32 v171, v133
	v_mov_b32_e32 v170, v132
	v_mov_b32_e32 v169, v135
	v_mov_b32_e32 v168, v134
	v_mov_b32_e32 v137, v141
	v_mov_b32_e32 v136, v140
	v_mov_b32_e32 v139, v143
	v_mov_b32_e32 v138, v142
	s_cbranch_vccnz .LBB0_163
	v_exp_f32_e32 v131, v142
	v_exp_f32_e32 v136, v143
	v_exp_f32_e32 v137, v140
	v_exp_f32_e32 v170, v132
	v_add_f32_e32 v131, 1.0, v131
	v_rcp_f32_e32 v138, v131
	v_exp_f32_e32 v131, v141
	v_add_f32_e32 v136, 1.0, v136
	v_rcp_f32_e32 v139, v136
	v_add_f32_e32 v136, 1.0, v137
	v_add_f32_e32 v131, 1.0, v131
	v_rcp_f32_e32 v137, v131
	v_exp_f32_e32 v131, v135
	v_exp_f32_e32 v168, v134
	v_exp_f32_e32 v171, v133
	v_rcp_f32_e32 v136, v136
	v_add_f32_e32 v131, 1.0, v131
	v_rcp_f32_e32 v169, v131
	v_add_f32_e32 v131, 1.0, v170
	v_add_f32_e32 v168, 1.0, v168
	v_rcp_f32_e32 v170, v131
	v_add_f32_e32 v131, 1.0, v171
	v_rcp_f32_e32 v168, v168
	v_rcp_f32_e32 v171, v131

.LBB0_172:
	v_cvt_pk_bf16_f32 v134, v140, v141
	v_cvt_pk_bf16_f32 v135, v138, v139
	s_nop 0
	v_cvt_pk_bf16_f32 v136, v168, v169
	v_cvt_pk_bf16_f32 v137, v170, v171
	global_store_dwordx4 v[132:133], v[134:137], off offset:256
	s_waitcnt vmcnt(9)
	v_mov_b32_e32 v130, v238
	s_and_b64 vcc, exec, s[8:9]
	s_mov_b64 s[88:89], -1
	s_waitcnt vmcnt(9)
	v_mul_f32_e32 v131, 0xbfb8aa3b, v130
	v_cndmask_b32_e64 v130, v130, v131, s[6:7]
	v_pk_mul_f32 v[140:141], v[94:95], v[130:131] op_sel_hi:[1,0]
	v_pk_mul_f32 v[142:143], v[92:93], v[130:131] op_sel_hi:[1,0]
	v_pk_mul_f32 v[132:133], v[90:91], v[130:131] op_sel_hi:[1,0]
	v_pk_mul_f32 v[134:135], v[88:89], v[130:131] op_sel_hi:[1,0]
	s_cbranch_vccnz .LBB0_176
	s_and_b64 vcc, exec, s[4:5]
	v_mov_b32_e32 v171, v133
	v_mov_b32_e32 v170, v132
	v_mov_b32_e32 v169, v135
	v_mov_b32_e32 v168, v134
	v_mov_b32_e32 v137, v141
	v_mov_b32_e32 v136, v140
	v_mov_b32_e32 v139, v143
	v_mov_b32_e32 v138, v142
	s_cbranch_vccnz .LBB0_175
	v_exp_f32_e32 v131, v142
	v_exp_f32_e32 v136, v143
	v_exp_f32_e32 v137, v140
	v_exp_f32_e32 v170, v132
	v_add_f32_e32 v131, 1.0, v131
	v_rcp_f32_e32 v138, v131
	v_exp_f32_e32 v131, v141
	v_add_f32_e32 v136, 1.0, v136
	v_rcp_f32_e32 v139, v136
	v_add_f32_e32 v136, 1.0, v137
	v_add_f32_e32 v131, 1.0, v131
	v_rcp_f32_e32 v137, v131
	v_exp_f32_e32 v131, v135
	v_exp_f32_e32 v168, v134
	v_exp_f32_e32 v171, v133
	v_rcp_f32_e32 v136, v136
	v_add_f32_e32 v131, 1.0, v131
	v_rcp_f32_e32 v169, v131
	v_add_f32_e32 v131, 1.0, v170
	v_add_f32_e32 v168, 1.0, v168
	v_rcp_f32_e32 v170, v131
	v_add_f32_e32 v131, 1.0, v171
	v_rcp_f32_e32 v168, v168
	v_rcp_f32_e32 v171, v131

.LBB0_184:
	v_cvt_pk_bf16_f32 v134, v140, v141
	v_cvt_pk_bf16_f32 v135, v138, v139
	s_nop 0
	v_cvt_pk_bf16_f32 v136, v168, v169
	v_cvt_pk_bf16_f32 v137, v170, v171
	global_store_dwordx4 v[132:133], v[134:137], off offset:256
	s_waitcnt vmcnt(10)
	v_mov_b32_e32 v130, v239
	s_and_b64 vcc, exec, s[8:9]
	s_mov_b64 s[88:89], -1
	s_waitcnt vmcnt(10)
	v_mul_f32_e32 v131, 0xbfb8aa3b, v130
	v_cndmask_b32_e64 v130, v130, v131, s[6:7]
	v_pk_mul_f32 v[140:141], v[78:79], v[130:131] op_sel_hi:[1,0]
	v_pk_mul_f32 v[142:143], v[76:77], v[130:131] op_sel_hi:[1,0]
	v_pk_mul_f32 v[132:133], v[74:75], v[130:131] op_sel_hi:[1,0]
	v_pk_mul_f32 v[134:135], v[72:73], v[130:131] op_sel_hi:[1,0]
	s_cbranch_vccnz .LBB0_188
	s_and_b64 vcc, exec, s[4:5]
	v_mov_b32_e32 v171, v133
	v_mov_b32_e32 v170, v132
	v_mov_b32_e32 v169, v135
	v_mov_b32_e32 v168, v134
	v_mov_b32_e32 v137, v141
	v_mov_b32_e32 v136, v140
	v_mov_b32_e32 v139, v143
	v_mov_b32_e32 v138, v142
	s_cbranch_vccnz .LBB0_187
	v_exp_f32_e32 v131, v142
	v_exp_f32_e32 v136, v143
	v_exp_f32_e32 v137, v140
	v_exp_f32_e32 v170, v132
	v_add_f32_e32 v131, 1.0, v131
	v_rcp_f32_e32 v138, v131
	v_exp_f32_e32 v131, v141
	v_add_f32_e32 v136, 1.0, v136
	v_rcp_f32_e32 v139, v136
	v_add_f32_e32 v136, 1.0, v137
	v_add_f32_e32 v131, 1.0, v131
	v_rcp_f32_e32 v137, v131
	v_exp_f32_e32 v131, v135
	v_exp_f32_e32 v168, v134
	v_exp_f32_e32 v171, v133
	v_rcp_f32_e32 v136, v136
	v_add_f32_e32 v131, 1.0, v131
	v_rcp_f32_e32 v169, v131
	v_add_f32_e32 v131, 1.0, v170
	v_add_f32_e32 v168, 1.0, v168
	v_rcp_f32_e32 v170, v131
	v_add_f32_e32 v131, 1.0, v171
	v_rcp_f32_e32 v168, v168
	v_rcp_f32_e32 v171, v131

.LBB0_196:
	v_cvt_pk_bf16_f32 v134, v140, v141
	v_cvt_pk_bf16_f32 v135, v138, v139
	s_nop 0
	v_cvt_pk_bf16_f32 v136, v168, v169
	v_cvt_pk_bf16_f32 v137, v170, v171
	global_store_dwordx4 v[132:133], v[134:137], off offset:256
	s_waitcnt vmcnt(11)
	v_mov_b32_e32 v130, v240
	s_and_b64 vcc, exec, s[8:9]
	s_mov_b64 s[88:89], -1
	s_waitcnt vmcnt(11)
	v_mul_f32_e32 v131, 0xbfb8aa3b, v130
	v_cndmask_b32_e64 v130, v130, v131, s[6:7]
	v_pk_mul_f32 v[140:141], v[62:63], v[130:131] op_sel_hi:[1,0]
	v_pk_mul_f32 v[142:143], v[60:61], v[130:131] op_sel_hi:[1,0]
	v_pk_mul_f32 v[132:133], v[58:59], v[130:131] op_sel_hi:[1,0]
	v_pk_mul_f32 v[134:135], v[56:57], v[130:131] op_sel_hi:[1,0]
	s_cbranch_vccnz .LBB0_200
	s_and_b64 vcc, exec, s[4:5]
	v_mov_b32_e32 v171, v133
	v_mov_b32_e32 v170, v132
	v_mov_b32_e32 v169, v135
	v_mov_b32_e32 v168, v134
	v_mov_b32_e32 v137, v141
	v_mov_b32_e32 v136, v140
	v_mov_b32_e32 v139, v143
	v_mov_b32_e32 v138, v142
	s_cbranch_vccnz .LBB0_199
	v_exp_f32_e32 v131, v142
	v_exp_f32_e32 v136, v143
	v_exp_f32_e32 v137, v140
	v_exp_f32_e32 v170, v132
	v_add_f32_e32 v131, 1.0, v131
	v_rcp_f32_e32 v138, v131
	v_exp_f32_e32 v131, v141
	v_add_f32_e32 v136, 1.0, v136
	v_rcp_f32_e32 v139, v136
	v_add_f32_e32 v136, 1.0, v137
	v_add_f32_e32 v131, 1.0, v131
	v_rcp_f32_e32 v137, v131
	v_exp_f32_e32 v131, v135
	v_exp_f32_e32 v168, v134
	v_exp_f32_e32 v171, v133
	v_rcp_f32_e32 v136, v136
	v_add_f32_e32 v131, 1.0, v131
	v_rcp_f32_e32 v169, v131
	v_add_f32_e32 v131, 1.0, v170
	v_add_f32_e32 v168, 1.0, v168
	v_rcp_f32_e32 v170, v131
	v_add_f32_e32 v131, 1.0, v171
	v_rcp_f32_e32 v168, v168
	v_rcp_f32_e32 v171, v131

.LBB0_208:
	v_cvt_pk_bf16_f32 v134, v140, v141
	v_cvt_pk_bf16_f32 v135, v138, v139
	s_nop 0
	v_cvt_pk_bf16_f32 v136, v168, v169
	v_cvt_pk_bf16_f32 v137, v170, v171
	global_store_dwordx4 v[132:133], v[134:137], off offset:256
	s_waitcnt vmcnt(12)
	v_mov_b32_e32 v130, v241
	s_and_b64 vcc, exec, s[8:9]
	s_mov_b64 s[88:89], -1
	s_waitcnt vmcnt(12)
	v_mul_f32_e32 v131, 0xbfb8aa3b, v130
	v_cndmask_b32_e64 v130, v130, v131, s[6:7]
	v_pk_mul_f32 v[140:141], v[46:47], v[130:131] op_sel_hi:[1,0]
	v_pk_mul_f32 v[142:143], v[44:45], v[130:131] op_sel_hi:[1,0]
	v_pk_mul_f32 v[132:133], v[42:43], v[130:131] op_sel_hi:[1,0]
	v_pk_mul_f32 v[134:135], v[40:41], v[130:131] op_sel_hi:[1,0]
	s_cbranch_vccnz .LBB0_212
	s_and_b64 vcc, exec, s[4:5]
	v_mov_b32_e32 v171, v133
	v_mov_b32_e32 v170, v132
	v_mov_b32_e32 v169, v135
	v_mov_b32_e32 v168, v134
	v_mov_b32_e32 v137, v141
	v_mov_b32_e32 v136, v140
	v_mov_b32_e32 v139, v143
	v_mov_b32_e32 v138, v142
	s_cbranch_vccnz .LBB0_211
	v_exp_f32_e32 v131, v142
	v_exp_f32_e32 v136, v143
	v_exp_f32_e32 v137, v140
	v_exp_f32_e32 v170, v132
	v_add_f32_e32 v131, 1.0, v131
	v_rcp_f32_e32 v138, v131
	v_exp_f32_e32 v131, v141
	v_add_f32_e32 v136, 1.0, v136
	v_rcp_f32_e32 v139, v136
	v_add_f32_e32 v136, 1.0, v137
	v_add_f32_e32 v131, 1.0, v131
	v_rcp_f32_e32 v137, v131
	v_exp_f32_e32 v131, v135
	v_exp_f32_e32 v168, v134
	v_exp_f32_e32 v171, v133
	v_rcp_f32_e32 v136, v136
	v_add_f32_e32 v131, 1.0, v131
	v_rcp_f32_e32 v169, v131
	v_add_f32_e32 v131, 1.0, v170
	v_add_f32_e32 v168, 1.0, v168
	v_rcp_f32_e32 v170, v131
	v_add_f32_e32 v131, 1.0, v171
	v_rcp_f32_e32 v168, v168
	v_rcp_f32_e32 v171, v131

.LBB0_220:
	v_cvt_pk_bf16_f32 v134, v140, v141
	v_cvt_pk_bf16_f32 v135, v138, v139
	s_nop 0
	v_cvt_pk_bf16_f32 v136, v168, v169
	v_cvt_pk_bf16_f32 v137, v170, v171
	global_store_dwordx4 v[132:133], v[134:137], off offset:256
	s_waitcnt vmcnt(13)
	v_mov_b32_e32 v130, v242
	s_and_b64 vcc, exec, s[8:9]
	s_mov_b64 s[88:89], -1
	s_waitcnt vmcnt(13)
	v_mul_f32_e32 v131, 0xbfb8aa3b, v130
	v_cndmask_b32_e64 v130, v130, v131, s[6:7]
	v_pk_mul_f32 v[140:141], v[30:31], v[130:131] op_sel_hi:[1,0]
	v_pk_mul_f32 v[142:143], v[28:29], v[130:131] op_sel_hi:[1,0]
	v_pk_mul_f32 v[132:133], v[26:27], v[130:131] op_sel_hi:[1,0]
	v_pk_mul_f32 v[134:135], v[24:25], v[130:131] op_sel_hi:[1,0]
	s_cbranch_vccnz .LBB0_224
	s_and_b64 vcc, exec, s[4:5]
	v_mov_b32_e32 v171, v133
	v_mov_b32_e32 v170, v132
	v_mov_b32_e32 v169, v135
	v_mov_b32_e32 v168, v134
	v_mov_b32_e32 v137, v141
	v_mov_b32_e32 v136, v140
	v_mov_b32_e32 v139, v143
	v_mov_b32_e32 v138, v142
	s_cbranch_vccnz .LBB0_223
	v_exp_f32_e32 v131, v142
	v_exp_f32_e32 v136, v143
	v_exp_f32_e32 v137, v140
	v_exp_f32_e32 v170, v132
	v_add_f32_e32 v131, 1.0, v131
	v_rcp_f32_e32 v138, v131
	v_exp_f32_e32 v131, v141
	v_add_f32_e32 v136, 1.0, v136
	v_rcp_f32_e32 v139, v136
	v_add_f32_e32 v136, 1.0, v137
	v_add_f32_e32 v131, 1.0, v131
	v_rcp_f32_e32 v137, v131
	v_exp_f32_e32 v131, v135
	v_exp_f32_e32 v168, v134
	v_exp_f32_e32 v171, v133
	v_rcp_f32_e32 v136, v136
	v_add_f32_e32 v131, 1.0, v131
	v_rcp_f32_e32 v169, v131
	v_add_f32_e32 v131, 1.0, v170
	v_add_f32_e32 v168, 1.0, v168
	v_rcp_f32_e32 v170, v131
	v_add_f32_e32 v131, 1.0, v171
	v_rcp_f32_e32 v168, v168
	v_rcp_f32_e32 v171, v131

.LBB0_232:
	v_cvt_pk_bf16_f32 v134, v140, v141
	v_cvt_pk_bf16_f32 v135, v138, v139
	s_nop 0
	v_cvt_pk_bf16_f32 v136, v168, v169
	v_cvt_pk_bf16_f32 v137, v170, v171
	global_store_dwordx4 v[132:133], v[134:137], off offset:256
	s_waitcnt vmcnt(14)
	v_mov_b32_e32 v128, v243
	s_and_b64 vcc, exec, s[8:9]
	s_waitcnt vmcnt(14)
	v_mul_f32_e32 v129, 0xbfb8aa3b, v128
	v_cndmask_b32_e64 v130, v128, v129, s[6:7]
	v_pk_mul_f32 v[138:139], v[14:15], v[130:131] op_sel_hi:[1,0]
	v_pk_mul_f32 v[140:141], v[12:13], v[130:131] op_sel_hi:[1,0]
	v_pk_mul_f32 v[128:129], v[10:11], v[130:131] op_sel_hi:[1,0]
	v_pk_mul_f32 v[132:133], v[8:9], v[130:131] op_sel_hi:[1,0]
	s_mov_b64 s[6:7], -1
	s_cbranch_vccnz .LBB0_236
	s_and_b64 vcc, exec, s[4:5]
	v_mov_b32_e32 v169, v129
	v_mov_b32_e32 v168, v128
	v_mov_b32_e32 v143, v133
	v_mov_b32_e32 v142, v132
	v_mov_b32_e32 v135, v139
	v_mov_b32_e32 v134, v138
	v_mov_b32_e32 v137, v141
	v_mov_b32_e32 v136, v140
	s_cbranch_vccnz .LBB0_235
	v_exp_f32_e32 v131, v140
	v_exp_f32_e32 v134, v141
	v_exp_f32_e32 v135, v138
	v_exp_f32_e32 v168, v128
	v_add_f32_e32 v131, 1.0, v131
	v_rcp_f32_e32 v136, v131
	v_exp_f32_e32 v131, v139
	v_add_f32_e32 v134, 1.0, v134
	v_rcp_f32_e32 v137, v134
	v_add_f32_e32 v134, 1.0, v135
	v_add_f32_e32 v131, 1.0, v131
	v_rcp_f32_e32 v135, v131
	v_exp_f32_e32 v131, v133
	v_exp_f32_e32 v142, v132
	v_exp_f32_e32 v169, v129
	v_rcp_f32_e32 v134, v134
	v_add_f32_e32 v131, 1.0, v131
	v_rcp_f32_e32 v143, v131
	v_add_f32_e32 v131, 1.0, v168
	v_add_f32_e32 v142, 1.0, v142
	v_rcp_f32_e32 v168, v131
	v_add_f32_e32 v131, 1.0, v169
	v_rcp_f32_e32 v142, v142
	v_rcp_f32_e32 v169, v131

.LBB0_392:
	s_lshl_b32 s40, s65, 8
	v_readlane_b32 s72, v249, 0
	s_ashr_i32 s41, s40, 31
	v_readlane_b32 s84, v249, 12
	v_readlane_b32 s85, v249, 13
	s_lshl_b64 s[40:41], s[40:41], 10
	v_readlane_b32 s86, v249, 14
	v_readlane_b32 s87, v249, 15
	s_mov_b64 s[28:29], s[84:85]
	s_add_u32 s40, s28, s40
	s_addc_u32 s41, s29, s41
	s_and_b64 s[42:43], s[0:1], exec
	s_cselect_b32 s67, s41, s45
	s_cselect_b32 s72, s40, s44
	s_ashr_i32 s39, s38, 31
	s_lshl_b64 s[42:43], s[38:39], 18
	s_add_u32 s42, s10, s42
	s_addc_u32 s43, s11, s43
	s_and_b64 s[48:49], s[0:1], exec
	v_readlane_b32 s73, v249, 1
	v_readlane_b32 s74, v249, 2
	s_cselect_b32 s39, s43, s47
	s_cselect_b32 s50, s42, s46
	s_add_u32 s51, s46, 0x100
	s_addc_u32 s73, s47, 0
	s_mov_b32 s74, -2
	s_waitcnt vmcnt(0)
	s_waitcnt lgkmcnt(0)
	v_readlane_b32 s75, v249, 3
	v_readlane_b32 s76, v249, 4
	v_readlane_b32 s77, v249, 5
	v_readlane_b32 s78, v249, 6
	v_readlane_b32 s79, v249, 7
	v_readlane_b32 s80, v249, 8
	v_readlane_b32 s81, v249, 9
	v_readlane_b32 s82, v249, 10
	v_readlane_b32 s83, v249, 11
	s_mov_b64 s[30:31], s[86:87]
	ds_read_b128 v[144:147], v153
	ds_read_b128 v[156:159], v153 offset:1024
	ds_read_b128 v[160:163], v153 offset:2048
	ds_read_b128 v[164:167], v153 offset:3072
	ds_read_b128 v[168:171], v154
	ds_read_b128 v[172:175], v154 offset:1024
	ds_read_b128 v[176:179], v154 offset:2048
	ds_read_b128 v[180:183], v154 offset:3072
	s_add_u32 s46, s44, 0x100
	s_addc_u32 s47, s45, 0
	s_cmp_eq_u32 s74, 4
	s_cselect_b32 s77, s67, s47
	s_cselect_b32 s76, s72, s46
	s_cselect_b32 s49, s39, s73
	s_cselect_b32 s48, s50, s51
	v_lshl_add_u64 v[148:149], s[44:45], 0, v[136:137]
	s_add_i32 m0, s52, 0xc000
	ds_read_b128 v[184:187], v155
	ds_read_b128 v[188:191], v155 offset:1024
	ds_read_b128 v[192:195], v155 offset:2048
	ds_read_b128 v[196:199], v155 offset:3072
	ds_read_b128 v[200:203], v155 offset:4096
	ds_read_b128 v[204:207], v155 offset:5120
	ds_read_b128 v[208:211], v155 offset:6144
	ds_read_b128 v[212:215], v155 offset:7168
	global_load_lds_dwordx4 v[148:149], off
	v_lshl_add_u64 v[148:149], s[44:45], 0, v[138:139]
	s_add_i32 m0, s52, 0xe000
	s_nop 0
	global_load_lds_dwordx4 v[148:149], off
	s_waitcnt vmcnt(8)
	s_waitcnt lgkmcnt(0)
	s_barrier
	s_setprio 1
	s_waitcnt lgkmcnt(0)
	v_mfma_f32_16x16x32_bf16 v[124:127], v[144:147], v[184:187], 0
	v_mfma_f32_16x16x32_bf16 v[120:123], v[160:163], v[184:187], 0
	v_mfma_f32_16x16x32_bf16 v[108:111], v[144:147], v[192:195], 0
	v_mfma_f32_16x16x32_bf16 v[104:107], v[160:163], v[192:195], 0
	v_mfma_f32_16x16x32_bf16 v[92:95], v[144:147], v[200:203], 0
	v_mfma_f32_16x16x32_bf16 v[88:91], v[160:163], v[200:203], 0
	v_mfma_f32_16x16x32_bf16 v[76:79], v[144:147], v[208:211], 0
	v_mfma_f32_16x16x32_bf16 v[72:75], v[160:163], v[208:211], 0
	v_mfma_f32_16x16x32_bf16 v[124:127], v[156:159], v[188:191], v[124:127]
	v_mfma_f32_16x16x32_bf16 v[120:123], v[164:167], v[188:191], v[120:123]
	v_mfma_f32_16x16x32_bf16 v[108:111], v[156:159], v[196:199], v[108:111]
	v_mfma_f32_16x16x32_bf16 v[104:107], v[164:167], v[196:199], v[104:107]
	v_mfma_f32_16x16x32_bf16 v[92:95], v[156:159], v[204:207], v[92:95]
	v_mfma_f32_16x16x32_bf16 v[88:91], v[164:167], v[204:207], v[88:91]
	v_mfma_f32_16x16x32_bf16 v[76:79], v[156:159], v[212:215], v[76:79]
	v_mfma_f32_16x16x32_bf16 v[72:75], v[164:167], v[212:215], v[72:75]
	s_setprio 0
	s_setprio 1
	v_mfma_f32_16x16x32_bf16 v[116:119], v[168:171], v[184:187], 0
	v_mfma_f32_16x16x32_bf16 v[112:115], v[176:179], v[184:187], 0
	v_mfma_f32_16x16x32_bf16 v[100:103], v[168:171], v[192:195], 0
	v_mfma_f32_16x16x32_bf16 v[96:99], v[176:179], v[192:195], 0
	v_mfma_f32_16x16x32_bf16 v[84:87], v[168:171], v[200:203], 0
	v_mfma_f32_16x16x32_bf16 v[80:83], v[176:179], v[200:203], 0
	v_mfma_f32_16x16x32_bf16 v[68:71], v[168:171], v[208:211], 0
	v_mfma_f32_16x16x32_bf16 v[64:67], v[176:179], v[208:211], 0
	v_mfma_f32_16x16x32_bf16 v[116:119], v[172:175], v[188:191], v[116:119]
	v_mfma_f32_16x16x32_bf16 v[112:115], v[180:183], v[188:191], v[112:115]
	v_mfma_f32_16x16x32_bf16 v[100:103], v[172:175], v[196:199], v[100:103]
	v_mfma_f32_16x16x32_bf16 v[96:99], v[180:183], v[196:199], v[96:99]
	v_mfma_f32_16x16x32_bf16 v[84:87], v[172:175], v[204:207], v[84:87]
	v_mfma_f32_16x16x32_bf16 v[80:83], v[180:183], v[204:207], v[80:83]
	v_mfma_f32_16x16x32_bf16 v[68:71], v[172:175], v[212:215], v[68:71]
	v_mfma_f32_16x16x32_bf16 v[64:67], v[180:183], v[212:215], v[64:67]
	s_setprio 0
	s_barrier
	s_add_i32 s44, s61, s33
	v_lshl_add_u64 v[148:149], s[48:49], 0, v[132:133]
	s_mov_b32 m0, s44
	ds_read_b128 v[184:187], v155 offset:16384
	ds_read_b128 v[188:191], v155 offset:17408
	ds_read_b128 v[192:195], v155 offset:18432
	ds_read_b128 v[196:199], v155 offset:19456
	ds_read_b128 v[200:203], v155 offset:20480
	ds_read_b128 v[204:207], v155 offset:21504
	ds_read_b128 v[208:211], v155 offset:22528
	ds_read_b128 v[212:215], v155 offset:23552
	global_load_lds_dwordx4 v[148:149], off
	s_add_i32 m0, s44, 0x2000
	s_add_u32 s44, s48, 0x20000
	v_lshl_add_u64 v[216:217], s[48:49], 0, v[128:129]
	s_addc_u32 s45, s49, 0
	s_add_i32 s68, s62, s33
	global_load_lds_dwordx4 v[216:217], off
	v_lshl_add_u64 v[220:221], s[44:45], 0, v[132:133]
	s_mov_b32 m0, s68
	v_lshl_add_u64 v[224:225], s[76:77], 0, v[130:131]
	global_load_lds_dwordx4 v[220:221], off
	v_lshl_add_u64 v[220:221], s[44:45], 0, v[128:129]
	s_add_i32 m0, s68, 0x2000
	v_lshl_add_u64 v[226:227], v[224:225], 0, s[8:9]
	global_load_lds_dwordx4 v[220:221], off
	v_lshl_add_u64 v[220:221], s[76:77], 0, v[134:135]
	s_mov_b32 m0, s52
	s_nop 0
	global_load_lds_dwordx4 v[220:221], off
	s_mov_b32 m0, s53
	s_nop 0
	global_load_lds_dwordx4 v[226:227], off
	s_waitcnt vmcnt(8)
	s_waitcnt lgkmcnt(0)
	s_barrier
	s_setprio 1
	s_waitcnt lgkmcnt(0)
	v_mfma_f32_16x16x32_bf16 v[60:63], v[144:147], v[184:187], 0
	v_mfma_f32_16x16x32_bf16 v[56:59], v[160:163], v[184:187], 0
	v_mfma_f32_16x16x32_bf16 v[44:47], v[144:147], v[192:195], 0
	v_mfma_f32_16x16x32_bf16 v[40:43], v[160:163], v[192:195], 0
	v_mfma_f32_16x16x32_bf16 v[28:31], v[144:147], v[200:203], 0
	v_mfma_f32_16x16x32_bf16 v[24:27], v[160:163], v[200:203], 0
	v_mfma_f32_16x16x32_bf16 v[12:15], v[144:147], v[208:211], 0
	v_mfma_f32_16x16x32_bf16 v[8:11], v[160:163], v[208:211], 0
	v_mfma_f32_16x16x32_bf16 v[60:63], v[156:159], v[188:191], v[60:63]
	v_mfma_f32_16x16x32_bf16 v[56:59], v[164:167], v[188:191], v[56:59]
	v_mfma_f32_16x16x32_bf16 v[44:47], v[156:159], v[196:199], v[44:47]
	v_mfma_f32_16x16x32_bf16 v[40:43], v[164:167], v[196:199], v[40:43]
	v_mfma_f32_16x16x32_bf16 v[28:31], v[156:159], v[204:207], v[28:31]
	v_mfma_f32_16x16x32_bf16 v[24:27], v[164:167], v[204:207], v[24:27]
	v_mfma_f32_16x16x32_bf16 v[12:15], v[156:159], v[212:215], v[12:15]
	v_mfma_f32_16x16x32_bf16 v[8:11], v[164:167], v[212:215], v[8:11]
	s_setprio 0
	s_setprio 1
	v_mfma_f32_16x16x32_bf16 v[52:55], v[168:171], v[184:187], 0
	v_mfma_f32_16x16x32_bf16 v[48:51], v[176:179], v[184:187], 0
	v_mfma_f32_16x16x32_bf16 v[36:39], v[168:171], v[192:195], 0
	v_mfma_f32_16x16x32_bf16 v[32:35], v[176:179], v[192:195], 0
	v_mfma_f32_16x16x32_bf16 v[20:23], v[168:171], v[200:203], 0
	v_mfma_f32_16x16x32_bf16 v[16:19], v[176:179], v[200:203], 0
	v_mfma_f32_16x16x32_bf16 v[4:7], v[168:171], v[208:211], 0
	v_mfma_f32_16x16x32_bf16 v[0:3], v[176:179], v[208:211], 0
	v_mfma_f32_16x16x32_bf16 v[52:55], v[172:175], v[188:191], v[52:55]
	v_mfma_f32_16x16x32_bf16 v[48:51], v[180:183], v[188:191], v[48:51]
	v_mfma_f32_16x16x32_bf16 v[36:39], v[172:175], v[196:199], v[36:39]
	v_mfma_f32_16x16x32_bf16 v[32:35], v[180:183], v[196:199], v[32:35]
	v_mfma_f32_16x16x32_bf16 v[20:23], v[172:175], v[204:207], v[20:23]
	v_mfma_f32_16x16x32_bf16 v[16:19], v[180:183], v[204:207], v[16:19]
	v_mfma_f32_16x16x32_bf16 v[4:7], v[172:175], v[212:215], v[4:7]
	v_mfma_f32_16x16x32_bf16 v[0:3], v[180:183], v[212:215], v[0:3]
	s_setprio 0
	s_barrier
	s_add_i32 s44, 0, 0x18000
	s_add_i32 s68, 0, 0x1c000
	v_add_u32_e32 v164, s44, v151
	v_add_u32_e32 v180, s68, v151
	ds_read_b128 v[144:147], v164
	ds_read_b128 v[156:159], v164 offset:1024
	ds_read_b128 v[160:163], v164 offset:2048
	ds_read_b128 v[164:167], v164 offset:3072
	ds_read_b128 v[168:171], v180
	ds_read_b128 v[172:175], v180 offset:1024
	ds_read_b128 v[176:179], v180 offset:2048
	ds_read_b128 v[180:183], v180 offset:3072
	s_mov_b32 m0, s54
	v_lshl_add_u64 v[226:227], v[220:221], 0, s[6:7]
	ds_read_b128 v[184:187], v155 offset:32768
	ds_read_b128 v[188:191], v155 offset:33792
	ds_read_b128 v[192:195], v155 offset:34816
	ds_read_b128 v[196:199], v155 offset:35840
	ds_read_b128 v[200:203], v155 offset:36864
	ds_read_b128 v[204:207], v155 offset:37888
	ds_read_b128 v[208:211], v155 offset:38912
	ds_read_b128 v[212:215], v155 offset:39936
	global_load_lds_dwordx4 v[226:227], off
	v_lshl_add_u64 v[226:227], v[224:225], 0, s[12:13]
	s_mov_b32 m0, s55
	s_nop 0
	global_load_lds_dwordx4 v[226:227], off
	s_waitcnt vmcnt(8)
	s_waitcnt lgkmcnt(0)
	s_barrier
	s_setprio 1
	s_waitcnt lgkmcnt(0)
	v_mfma_f32_16x16x32_bf16 v[124:127], v[144:147], v[184:187], v[124:127]
	v_mfma_f32_16x16x32_bf16 v[120:123], v[160:163], v[184:187], v[120:123]
	v_mfma_f32_16x16x32_bf16 v[108:111], v[144:147], v[192:195], v[108:111]
	v_mfma_f32_16x16x32_bf16 v[104:107], v[160:163], v[192:195], v[104:107]
	v_mfma_f32_16x16x32_bf16 v[92:95], v[144:147], v[200:203], v[92:95]
	v_mfma_f32_16x16x32_bf16 v[88:91], v[160:163], v[200:203], v[88:91]
	v_mfma_f32_16x16x32_bf16 v[76:79], v[144:147], v[208:211], v[76:79]
	v_mfma_f32_16x16x32_bf16 v[72:75], v[160:163], v[208:211], v[72:75]
	v_mfma_f32_16x16x32_bf16 v[124:127], v[156:159], v[188:191], v[124:127]
	v_mfma_f32_16x16x32_bf16 v[120:123], v[164:167], v[188:191], v[120:123]
	v_mfma_f32_16x16x32_bf16 v[108:111], v[156:159], v[196:199], v[108:111]
	v_mfma_f32_16x16x32_bf16 v[104:107], v[164:167], v[196:199], v[104:107]
	v_mfma_f32_16x16x32_bf16 v[92:95], v[156:159], v[204:207], v[92:95]
	v_mfma_f32_16x16x32_bf16 v[88:91], v[164:167], v[204:207], v[88:91]
	v_mfma_f32_16x16x32_bf16 v[76:79], v[156:159], v[212:215], v[76:79]
	v_mfma_f32_16x16x32_bf16 v[72:75], v[164:167], v[212:215], v[72:75]
	s_setprio 0
	s_setprio 1
	v_mfma_f32_16x16x32_bf16 v[116:119], v[168:171], v[184:187], v[116:119]
	v_mfma_f32_16x16x32_bf16 v[112:115], v[176:179], v[184:187], v[112:115]
	v_mfma_f32_16x16x32_bf16 v[100:103], v[168:171], v[192:195], v[100:103]
	v_mfma_f32_16x16x32_bf16 v[96:99], v[176:179], v[192:195], v[96:99]
	v_mfma_f32_16x16x32_bf16 v[84:87], v[168:171], v[200:203], v[84:87]
	v_mfma_f32_16x16x32_bf16 v[80:83], v[176:179], v[200:203], v[80:83]
	v_mfma_f32_16x16x32_bf16 v[68:71], v[168:171], v[208:211], v[68:71]
	v_mfma_f32_16x16x32_bf16 v[64:67], v[176:179], v[208:211], v[64:67]
	v_mfma_f32_16x16x32_bf16 v[116:119], v[172:175], v[188:191], v[116:119]
	v_mfma_f32_16x16x32_bf16 v[112:115], v[180:183], v[188:191], v[112:115]
	v_mfma_f32_16x16x32_bf16 v[100:103], v[172:175], v[196:199], v[100:103]
	v_mfma_f32_16x16x32_bf16 v[96:99], v[180:183], v[196:199], v[96:99]
	v_mfma_f32_16x16x32_bf16 v[84:87], v[172:175], v[204:207], v[84:87]
	v_mfma_f32_16x16x32_bf16 v[80:83], v[180:183], v[204:207], v[80:83]
	v_mfma_f32_16x16x32_bf16 v[68:71], v[172:175], v[212:215], v[68:71]
	v_mfma_f32_16x16x32_bf16 v[64:67], v[180:183], v[212:215], v[64:67]
	s_setprio 0
	s_barrier
	s_add_i32 s44, s44, s33
	v_lshl_add_u64 v[148:149], v[148:149], 0, s[22:23]
	s_mov_b32 m0, s44
	ds_read_b128 v[184:187], v155 offset:49152
	ds_read_b128 v[188:191], v155 offset:50176
	ds_read_b128 v[192:195], v155 offset:51200
	ds_read_b128 v[196:199], v155 offset:52224
	ds_read_b128 v[200:203], v155 offset:53248
	ds_read_b128 v[204:207], v155 offset:54272
	ds_read_b128 v[208:211], v155 offset:55296
	ds_read_b128 v[212:215], v155 offset:56320
	global_load_lds_dwordx4 v[148:149], off
	s_add_i32 m0, s44, 0x2000
	s_add_u32 s44, s48, 0x20080
	v_lshl_add_u64 v[148:149], v[216:217], 0, s[22:23]
	s_addc_u32 s45, s49, 0
	s_add_i32 s48, s68, s33
	global_load_lds_dwordx4 v[148:149], off
	v_lshl_add_u64 v[148:149], s[44:45], 0, v[132:133]
	s_mov_b32 m0, s48
	s_nop 0
	global_load_lds_dwordx4 v[148:149], off
	v_lshl_add_u64 v[148:149], s[44:45], 0, v[128:129]
	s_add_i32 m0, s48, 0x2000
	s_nop 0
	global_load_lds_dwordx4 v[148:149], off
	v_lshl_add_u64 v[148:149], v[220:221], 0, s[22:23]
	s_mov_b32 m0, s57
	s_nop 0
	global_load_lds_dwordx4 v[148:149], off
	v_lshl_add_u64 v[148:149], v[224:225], 0, s[24:25]
	s_mov_b32 m0, s58
	s_nop 0
	global_load_lds_dwordx4 v[148:149], off
	s_waitcnt vmcnt(8)
	s_waitcnt lgkmcnt(0)
	s_barrier
	s_setprio 1
	s_waitcnt lgkmcnt(0)
	v_mfma_f32_16x16x32_bf16 v[60:63], v[144:147], v[184:187], v[60:63]
	v_mfma_f32_16x16x32_bf16 v[56:59], v[160:163], v[184:187], v[56:59]
	v_mfma_f32_16x16x32_bf16 v[44:47], v[144:147], v[192:195], v[44:47]
	v_mfma_f32_16x16x32_bf16 v[40:43], v[160:163], v[192:195], v[40:43]
	v_mfma_f32_16x16x32_bf16 v[28:31], v[144:147], v[200:203], v[28:31]
	v_mfma_f32_16x16x32_bf16 v[24:27], v[160:163], v[200:203], v[24:27]
	v_mfma_f32_16x16x32_bf16 v[12:15], v[144:147], v[208:211], v[12:15]
	v_mfma_f32_16x16x32_bf16 v[8:11], v[160:163], v[208:211], v[8:11]
	v_mfma_f32_16x16x32_bf16 v[60:63], v[156:159], v[188:191], v[60:63]
	v_mfma_f32_16x16x32_bf16 v[56:59], v[164:167], v[188:191], v[56:59]
	v_mfma_f32_16x16x32_bf16 v[44:47], v[156:159], v[196:199], v[44:47]
	v_mfma_f32_16x16x32_bf16 v[40:43], v[164:167], v[196:199], v[40:43]
	v_mfma_f32_16x16x32_bf16 v[28:31], v[156:159], v[204:207], v[28:31]
	v_mfma_f32_16x16x32_bf16 v[24:27], v[164:167], v[204:207], v[24:27]
	v_mfma_f32_16x16x32_bf16 v[12:15], v[156:159], v[212:215], v[12:15]
	v_mfma_f32_16x16x32_bf16 v[8:11], v[164:167], v[212:215], v[8:11]
	s_setprio 0
	s_setprio 1
	v_mfma_f32_16x16x32_bf16 v[52:55], v[168:171], v[184:187], v[52:55]
	v_mfma_f32_16x16x32_bf16 v[48:51], v[176:179], v[184:187], v[48:51]
	v_mfma_f32_16x16x32_bf16 v[36:39], v[168:171], v[192:195], v[36:39]
	v_mfma_f32_16x16x32_bf16 v[32:35], v[176:179], v[192:195], v[32:35]
	v_mfma_f32_16x16x32_bf16 v[20:23], v[168:171], v[200:203], v[20:23]
	v_mfma_f32_16x16x32_bf16 v[16:19], v[176:179], v[200:203], v[16:19]
	v_mfma_f32_16x16x32_bf16 v[4:7], v[168:171], v[208:211], v[4:7]
	v_mfma_f32_16x16x32_bf16 v[0:3], v[176:179], v[208:211], v[0:3]
	v_mfma_f32_16x16x32_bf16 v[52:55], v[172:175], v[188:191], v[52:55]
	v_mfma_f32_16x16x32_bf16 v[48:51], v[180:183], v[188:191], v[48:51]
	v_mfma_f32_16x16x32_bf16 v[36:39], v[172:175], v[196:199], v[36:39]
	v_mfma_f32_16x16x32_bf16 v[32:35], v[180:183], v[196:199], v[32:35]
	v_mfma_f32_16x16x32_bf16 v[20:23], v[172:175], v[204:207], v[20:23]
	v_mfma_f32_16x16x32_bf16 v[16:19], v[180:183], v[204:207], v[16:19]
	v_mfma_f32_16x16x32_bf16 v[4:7], v[172:175], v[212:215], v[4:7]
	v_mfma_f32_16x16x32_bf16 v[0:3], v[180:183], v[212:215], v[0:3]
	s_setprio 0
	s_barrier
	s_add_i32 s74, s74, 2
	s_add_u32 s51, s51, 0x100
	s_addc_u32 s73, s73, 0
	s_cmp_gt_u32 s74, 5
	s_mov_b64 s[44:45], s[46:47]

.LBB0_465:
	s_lshl_b32 s42, s73, 8
	s_ashr_i32 s43, s42, 31
	s_lshl_b64 s[42:43], s[42:43], 11
	s_add_u32 s42, s10, s42
	s_addc_u32 s43, s11, s43
	s_and_b64 s[44:45], s[4:5], exec
	s_cselect_b32 s47, s43, s49
	s_cselect_b32 s74, s42, s48
	s_ashr_i32 s41, s40, 31
	s_lshl_b64 s[44:45], s[40:41], 19
	s_add_u32 s44, s33, s44
	s_addc_u32 s45, s34, s45
	s_and_b64 s[50:51], s[4:5], exec
	s_cselect_b32 s41, s45, s53
	s_cselect_b32 s50, s44, s52
	s_add_u32 s51, s52, 0x100
	s_addc_u32 s75, s53, 0
	s_mov_b32 s76, -2
	s_waitcnt lgkmcnt(0)
	s_waitcnt vmcnt(0)
	s_waitcnt lgkmcnt(0)
	ds_read_b128 v[144:147], v151
	ds_read_b128 v[156:159], v151 offset:1024
	ds_read_b128 v[160:163], v151 offset:2048
	ds_read_b128 v[164:167], v151 offset:3072
	ds_read_b128 v[168:171], v152
	ds_read_b128 v[172:175], v152 offset:1024
	ds_read_b128 v[176:179], v152 offset:2048
	ds_read_b128 v[180:183], v152 offset:3072
	s_add_u32 s52, s48, 0x100
	s_addc_u32 s53, s49, 0
	s_cmp_eq_u32 s76, 12
	s_cselect_b32 s79, s47, s53
	s_cselect_b32 s78, s74, s52
	s_cselect_b32 s55, s41, s75
	s_cselect_b32 s54, s50, s51
	v_lshl_add_u64 v[216:217], s[48:49], 0, v[136:137]
	s_add_i32 m0, s56, 0xc000
	ds_read_b128 v[184:187], v153
	ds_read_b128 v[188:191], v153 offset:1024
	ds_read_b128 v[192:195], v153 offset:2048
	ds_read_b128 v[196:199], v153 offset:3072
	ds_read_b128 v[200:203], v153 offset:4096
	ds_read_b128 v[204:207], v153 offset:5120
	ds_read_b128 v[208:211], v153 offset:6144
	ds_read_b128 v[212:215], v153 offset:7168
	global_load_lds_dwordx4 v[216:217], off
	v_lshl_add_u64 v[216:217], s[48:49], 0, v[138:139]
	s_add_i32 m0, s56, 0xe000
	s_nop 0
	global_load_lds_dwordx4 v[216:217], off
	s_waitcnt vmcnt(8)
	s_waitcnt lgkmcnt(0)
	s_barrier
	s_setprio 1
	s_waitcnt lgkmcnt(0)
	v_mfma_f32_16x16x32_bf16 v[124:127], v[144:147], v[184:187], 0
	v_mfma_f32_16x16x32_bf16 v[120:123], v[160:163], v[184:187], 0
	v_mfma_f32_16x16x32_bf16 v[108:111], v[144:147], v[192:195], 0
	v_mfma_f32_16x16x32_bf16 v[104:107], v[160:163], v[192:195], 0
	v_mfma_f32_16x16x32_bf16 v[92:95], v[144:147], v[200:203], 0
	v_mfma_f32_16x16x32_bf16 v[88:91], v[160:163], v[200:203], 0
	v_mfma_f32_16x16x32_bf16 v[76:79], v[144:147], v[208:211], 0
	v_mfma_f32_16x16x32_bf16 v[72:75], v[160:163], v[208:211], 0
	v_mfma_f32_16x16x32_bf16 v[124:127], v[156:159], v[188:191], v[124:127]
	v_mfma_f32_16x16x32_bf16 v[120:123], v[164:167], v[188:191], v[120:123]
	v_mfma_f32_16x16x32_bf16 v[108:111], v[156:159], v[196:199], v[108:111]
	v_mfma_f32_16x16x32_bf16 v[104:107], v[164:167], v[196:199], v[104:107]
	v_mfma_f32_16x16x32_bf16 v[92:95], v[156:159], v[204:207], v[92:95]
	v_mfma_f32_16x16x32_bf16 v[88:91], v[164:167], v[204:207], v[88:91]
	v_mfma_f32_16x16x32_bf16 v[76:79], v[156:159], v[212:215], v[76:79]
	v_mfma_f32_16x16x32_bf16 v[72:75], v[164:167], v[212:215], v[72:75]
	s_setprio 0
	s_setprio 1
	v_mfma_f32_16x16x32_bf16 v[116:119], v[168:171], v[184:187], 0
	v_mfma_f32_16x16x32_bf16 v[112:115], v[176:179], v[184:187], 0
	v_mfma_f32_16x16x32_bf16 v[100:103], v[168:171], v[192:195], 0
	v_mfma_f32_16x16x32_bf16 v[96:99], v[176:179], v[192:195], 0
	v_mfma_f32_16x16x32_bf16 v[84:87], v[168:171], v[200:203], 0
	v_mfma_f32_16x16x32_bf16 v[80:83], v[176:179], v[200:203], 0
	v_mfma_f32_16x16x32_bf16 v[68:71], v[168:171], v[208:211], 0
	v_mfma_f32_16x16x32_bf16 v[64:67], v[176:179], v[208:211], 0
	v_mfma_f32_16x16x32_bf16 v[116:119], v[172:175], v[188:191], v[116:119]
	v_mfma_f32_16x16x32_bf16 v[112:115], v[180:183], v[188:191], v[112:115]
	v_mfma_f32_16x16x32_bf16 v[100:103], v[172:175], v[196:199], v[100:103]
	v_mfma_f32_16x16x32_bf16 v[96:99], v[180:183], v[196:199], v[96:99]
	v_mfma_f32_16x16x32_bf16 v[84:87], v[172:175], v[204:207], v[84:87]
	v_mfma_f32_16x16x32_bf16 v[80:83], v[180:183], v[204:207], v[80:83]
	v_mfma_f32_16x16x32_bf16 v[68:71], v[172:175], v[212:215], v[68:71]
	v_mfma_f32_16x16x32_bf16 v[64:67], v[180:183], v[212:215], v[64:67]
	s_setprio 0
	s_barrier
	s_add_i32 s48, s67, s35
	v_lshl_add_u64 v[216:217], s[54:55], 0, v[130:131]
	s_mov_b32 m0, s48
	ds_read_b128 v[184:187], v153 offset:16384
	ds_read_b128 v[188:191], v153 offset:17408
	ds_read_b128 v[192:195], v153 offset:18432
	ds_read_b128 v[196:199], v153 offset:19456
	ds_read_b128 v[200:203], v153 offset:20480
	ds_read_b128 v[204:207], v153 offset:21504
	ds_read_b128 v[208:211], v153 offset:22528
	ds_read_b128 v[212:215], v153 offset:23552
	global_load_lds_dwordx4 v[216:217], off
	s_add_i32 m0, s48, 0x2000
	s_add_u32 s48, s54, 0x40000
	v_lshl_add_u64 v[220:221], s[54:55], 0, v[134:135]
	s_addc_u32 s49, s55, 0
	s_add_i32 s68, s72, s35
	global_load_lds_dwordx4 v[220:221], off
	v_lshl_add_u64 v[224:225], s[48:49], 0, v[130:131]
	s_mov_b32 m0, s68
	v_lshl_add_u64 v[226:227], s[78:79], 0, v[132:133]
	global_load_lds_dwordx4 v[224:225], off
	v_lshl_add_u64 v[224:225], s[48:49], 0, v[134:135]
	s_add_i32 m0, s68, 0x2000
	v_lshl_add_u64 v[228:229], v[226:227], 0, s[12:13]
	global_load_lds_dwordx4 v[224:225], off
	v_lshl_add_u64 v[224:225], s[78:79], 0, v[128:129]
	s_mov_b32 m0, s56
	s_nop 0
	global_load_lds_dwordx4 v[224:225], off
	s_mov_b32 m0, s57
	s_nop 0
	global_load_lds_dwordx4 v[228:229], off
	s_waitcnt vmcnt(8)
	s_waitcnt lgkmcnt(0)
	s_barrier
	s_setprio 1
	s_waitcnt lgkmcnt(0)
	v_mfma_f32_16x16x32_bf16 v[60:63], v[144:147], v[184:187], 0
	v_mfma_f32_16x16x32_bf16 v[56:59], v[160:163], v[184:187], 0
	v_mfma_f32_16x16x32_bf16 v[44:47], v[144:147], v[192:195], 0
	v_mfma_f32_16x16x32_bf16 v[40:43], v[160:163], v[192:195], 0
	v_mfma_f32_16x16x32_bf16 v[28:31], v[144:147], v[200:203], 0
	v_mfma_f32_16x16x32_bf16 v[24:27], v[160:163], v[200:203], 0
	v_mfma_f32_16x16x32_bf16 v[12:15], v[144:147], v[208:211], 0
	v_mfma_f32_16x16x32_bf16 v[8:11], v[160:163], v[208:211], 0
	v_mfma_f32_16x16x32_bf16 v[60:63], v[156:159], v[188:191], v[60:63]
	v_mfma_f32_16x16x32_bf16 v[56:59], v[164:167], v[188:191], v[56:59]
	v_mfma_f32_16x16x32_bf16 v[44:47], v[156:159], v[196:199], v[44:47]
	v_mfma_f32_16x16x32_bf16 v[40:43], v[164:167], v[196:199], v[40:43]
	v_mfma_f32_16x16x32_bf16 v[28:31], v[156:159], v[204:207], v[28:31]
	v_mfma_f32_16x16x32_bf16 v[24:27], v[164:167], v[204:207], v[24:27]
	v_mfma_f32_16x16x32_bf16 v[12:15], v[156:159], v[212:215], v[12:15]
	v_mfma_f32_16x16x32_bf16 v[8:11], v[164:167], v[212:215], v[8:11]
	s_setprio 0
	s_setprio 1
	v_mfma_f32_16x16x32_bf16 v[52:55], v[168:171], v[184:187], 0
	v_mfma_f32_16x16x32_bf16 v[48:51], v[176:179], v[184:187], 0
	v_mfma_f32_16x16x32_bf16 v[36:39], v[168:171], v[192:195], 0
	v_mfma_f32_16x16x32_bf16 v[32:35], v[176:179], v[192:195], 0
	v_mfma_f32_16x16x32_bf16 v[20:23], v[168:171], v[200:203], 0
	v_mfma_f32_16x16x32_bf16 v[16:19], v[176:179], v[200:203], 0
	v_mfma_f32_16x16x32_bf16 v[4:7], v[168:171], v[208:211], 0
	v_mfma_f32_16x16x32_bf16 v[0:3], v[176:179], v[208:211], 0
	v_mfma_f32_16x16x32_bf16 v[52:55], v[172:175], v[188:191], v[52:55]
	v_mfma_f32_16x16x32_bf16 v[48:51], v[180:183], v[188:191], v[48:51]
	v_mfma_f32_16x16x32_bf16 v[36:39], v[172:175], v[196:199], v[36:39]
	v_mfma_f32_16x16x32_bf16 v[32:35], v[180:183], v[196:199], v[32:35]
	v_mfma_f32_16x16x32_bf16 v[20:23], v[172:175], v[204:207], v[20:23]
	v_mfma_f32_16x16x32_bf16 v[16:19], v[180:183], v[204:207], v[16:19]
	v_mfma_f32_16x16x32_bf16 v[4:7], v[172:175], v[212:215], v[4:7]
	v_mfma_f32_16x16x32_bf16 v[0:3], v[180:183], v[212:215], v[0:3]
	s_setprio 0
	s_barrier
	s_add_i32 s48, 0, 0x18000
	v_add_u32_e32 v155, s48, v149
	s_add_i32 s68, 0, 0x1c000
	ds_read_b128 v[144:147], v155
	ds_read_b128 v[156:159], v155 offset:1024
	ds_read_b128 v[160:163], v155 offset:2048
	ds_read_b128 v[164:167], v155 offset:3072
	v_add_u32_e32 v155, s68, v149
	ds_read_b128 v[168:171], v155
	ds_read_b128 v[172:175], v155 offset:1024
	ds_read_b128 v[176:179], v155 offset:2048
	ds_read_b128 v[180:183], v155 offset:3072
	s_mov_b32 m0, s58
	v_lshl_add_u64 v[228:229], v[224:225], 0, s[8:9]
	ds_read_b128 v[184:187], v153 offset:32768
	ds_read_b128 v[188:191], v153 offset:33792
	ds_read_b128 v[192:195], v153 offset:34816
	ds_read_b128 v[196:199], v153 offset:35840
	ds_read_b128 v[200:203], v153 offset:36864
	ds_read_b128 v[204:207], v153 offset:37888
	ds_read_b128 v[208:211], v153 offset:38912
	ds_read_b128 v[212:215], v153 offset:39936
	global_load_lds_dwordx4 v[228:229], off
	v_lshl_add_u64 v[228:229], v[226:227], 0, s[14:15]
	s_mov_b32 m0, s59
	s_nop 0
	global_load_lds_dwordx4 v[228:229], off
	s_waitcnt vmcnt(8)
	s_waitcnt lgkmcnt(0)
	s_barrier
	s_setprio 1
	s_waitcnt lgkmcnt(0)
	v_mfma_f32_16x16x32_bf16 v[124:127], v[144:147], v[184:187], v[124:127]
	v_mfma_f32_16x16x32_bf16 v[120:123], v[160:163], v[184:187], v[120:123]
	v_mfma_f32_16x16x32_bf16 v[108:111], v[144:147], v[192:195], v[108:111]
	v_mfma_f32_16x16x32_bf16 v[104:107], v[160:163], v[192:195], v[104:107]
	v_mfma_f32_16x16x32_bf16 v[92:95], v[144:147], v[200:203], v[92:95]
	v_mfma_f32_16x16x32_bf16 v[88:91], v[160:163], v[200:203], v[88:91]
	v_mfma_f32_16x16x32_bf16 v[76:79], v[144:147], v[208:211], v[76:79]
	v_mfma_f32_16x16x32_bf16 v[72:75], v[160:163], v[208:211], v[72:75]
	v_mfma_f32_16x16x32_bf16 v[124:127], v[156:159], v[188:191], v[124:127]
	v_mfma_f32_16x16x32_bf16 v[120:123], v[164:167], v[188:191], v[120:123]
	v_mfma_f32_16x16x32_bf16 v[108:111], v[156:159], v[196:199], v[108:111]
	v_mfma_f32_16x16x32_bf16 v[104:107], v[164:167], v[196:199], v[104:107]
	v_mfma_f32_16x16x32_bf16 v[92:95], v[156:159], v[204:207], v[92:95]
	v_mfma_f32_16x16x32_bf16 v[88:91], v[164:167], v[204:207], v[88:91]
	v_mfma_f32_16x16x32_bf16 v[76:79], v[156:159], v[212:215], v[76:79]
	v_mfma_f32_16x16x32_bf16 v[72:75], v[164:167], v[212:215], v[72:75]
	s_setprio 0
	s_setprio 1
	v_mfma_f32_16x16x32_bf16 v[116:119], v[168:171], v[184:187], v[116:119]
	v_mfma_f32_16x16x32_bf16 v[112:115], v[176:179], v[184:187], v[112:115]
	v_mfma_f32_16x16x32_bf16 v[100:103], v[168:171], v[192:195], v[100:103]
	v_mfma_f32_16x16x32_bf16 v[96:99], v[176:179], v[192:195], v[96:99]
	v_mfma_f32_16x16x32_bf16 v[84:87], v[168:171], v[200:203], v[84:87]
	v_mfma_f32_16x16x32_bf16 v[80:83], v[176:179], v[200:203], v[80:83]
	v_mfma_f32_16x16x32_bf16 v[68:71], v[168:171], v[208:211], v[68:71]
	v_mfma_f32_16x16x32_bf16 v[64:67], v[176:179], v[208:211], v[64:67]
	v_mfma_f32_16x16x32_bf16 v[116:119], v[172:175], v[188:191], v[116:119]
	v_mfma_f32_16x16x32_bf16 v[112:115], v[180:183], v[188:191], v[112:115]
	v_mfma_f32_16x16x32_bf16 v[100:103], v[172:175], v[196:199], v[100:103]
	v_mfma_f32_16x16x32_bf16 v[96:99], v[180:183], v[196:199], v[96:99]
	v_mfma_f32_16x16x32_bf16 v[84:87], v[172:175], v[204:207], v[84:87]
	v_mfma_f32_16x16x32_bf16 v[80:83], v[180:183], v[204:207], v[80:83]
	v_mfma_f32_16x16x32_bf16 v[68:71], v[172:175], v[212:215], v[68:71]
	v_mfma_f32_16x16x32_bf16 v[64:67], v[180:183], v[212:215], v[64:67]
	s_setprio 0
	s_barrier
	s_add_i32 s48, s48, s35
	v_lshl_add_u64 v[216:217], v[216:217], 0, s[24:25]
	s_mov_b32 m0, s48
	ds_read_b128 v[184:187], v153 offset:49152
	ds_read_b128 v[188:191], v153 offset:50176
	ds_read_b128 v[192:195], v153 offset:51200
	ds_read_b128 v[196:199], v153 offset:52224
	ds_read_b128 v[200:203], v153 offset:53248
	ds_read_b128 v[204:207], v153 offset:54272
	ds_read_b128 v[208:211], v153 offset:55296
	ds_read_b128 v[212:215], v153 offset:56320
	global_load_lds_dwordx4 v[216:217], off
	s_add_i32 m0, s48, 0x2000
	s_add_u32 s48, s54, 0x40080
	v_lshl_add_u64 v[216:217], v[220:221], 0, s[24:25]
	s_addc_u32 s49, s55, 0
	s_add_i32 s54, s68, s35
	global_load_lds_dwordx4 v[216:217], off
	v_lshl_add_u64 v[216:217], s[48:49], 0, v[130:131]
	s_mov_b32 m0, s54
	s_nop 0
	global_load_lds_dwordx4 v[216:217], off
	v_lshl_add_u64 v[216:217], s[48:49], 0, v[134:135]
	s_add_i32 m0, s54, 0x2000
	s_nop 0
	global_load_lds_dwordx4 v[216:217], off
	v_lshl_add_u64 v[216:217], v[224:225], 0, s[24:25]
	s_mov_b32 m0, s61
	s_nop 0
	global_load_lds_dwordx4 v[216:217], off
	v_lshl_add_u64 v[216:217], v[226:227], 0, s[36:37]
	s_mov_b32 m0, s62
	s_nop 0
	global_load_lds_dwordx4 v[216:217], off
	s_waitcnt vmcnt(8)
	s_waitcnt lgkmcnt(0)
	s_barrier
	s_setprio 1
	s_waitcnt lgkmcnt(0)
	v_mfma_f32_16x16x32_bf16 v[60:63], v[144:147], v[184:187], v[60:63]
	v_mfma_f32_16x16x32_bf16 v[56:59], v[160:163], v[184:187], v[56:59]
	v_mfma_f32_16x16x32_bf16 v[44:47], v[144:147], v[192:195], v[44:47]
	v_mfma_f32_16x16x32_bf16 v[40:43], v[160:163], v[192:195], v[40:43]
	v_mfma_f32_16x16x32_bf16 v[28:31], v[144:147], v[200:203], v[28:31]
	v_mfma_f32_16x16x32_bf16 v[24:27], v[160:163], v[200:203], v[24:27]
	v_mfma_f32_16x16x32_bf16 v[12:15], v[144:147], v[208:211], v[12:15]
	v_mfma_f32_16x16x32_bf16 v[8:11], v[160:163], v[208:211], v[8:11]
	v_mfma_f32_16x16x32_bf16 v[60:63], v[156:159], v[188:191], v[60:63]
	v_mfma_f32_16x16x32_bf16 v[56:59], v[164:167], v[188:191], v[56:59]
	v_mfma_f32_16x16x32_bf16 v[44:47], v[156:159], v[196:199], v[44:47]
	v_mfma_f32_16x16x32_bf16 v[40:43], v[164:167], v[196:199], v[40:43]
	v_mfma_f32_16x16x32_bf16 v[28:31], v[156:159], v[204:207], v[28:31]
	v_mfma_f32_16x16x32_bf16 v[24:27], v[164:167], v[204:207], v[24:27]
	v_mfma_f32_16x16x32_bf16 v[12:15], v[156:159], v[212:215], v[12:15]
	v_mfma_f32_16x16x32_bf16 v[8:11], v[164:167], v[212:215], v[8:11]
	s_setprio 0
	s_setprio 1
	v_mfma_f32_16x16x32_bf16 v[52:55], v[168:171], v[184:187], v[52:55]
	v_mfma_f32_16x16x32_bf16 v[48:51], v[176:179], v[184:187], v[48:51]
	v_mfma_f32_16x16x32_bf16 v[36:39], v[168:171], v[192:195], v[36:39]
	v_mfma_f32_16x16x32_bf16 v[32:35], v[176:179], v[192:195], v[32:35]
	v_mfma_f32_16x16x32_bf16 v[20:23], v[168:171], v[200:203], v[20:23]
	v_mfma_f32_16x16x32_bf16 v[16:19], v[176:179], v[200:203], v[16:19]
	v_mfma_f32_16x16x32_bf16 v[4:7], v[168:171], v[208:211], v[4:7]
	v_mfma_f32_16x16x32_bf16 v[0:3], v[176:179], v[208:211], v[0:3]
	v_mfma_f32_16x16x32_bf16 v[52:55], v[172:175], v[188:191], v[52:55]
	v_mfma_f32_16x16x32_bf16 v[48:51], v[180:183], v[188:191], v[48:51]
	v_mfma_f32_16x16x32_bf16 v[36:39], v[172:175], v[196:199], v[36:39]
	v_mfma_f32_16x16x32_bf16 v[32:35], v[180:183], v[196:199], v[32:35]
	v_mfma_f32_16x16x32_bf16 v[20:23], v[172:175], v[204:207], v[20:23]
	v_mfma_f32_16x16x32_bf16 v[16:19], v[180:183], v[204:207], v[16:19]
	v_mfma_f32_16x16x32_bf16 v[4:7], v[172:175], v[212:215], v[4:7]
	v_mfma_f32_16x16x32_bf16 v[0:3], v[180:183], v[212:215], v[0:3]
	s_setprio 0
	s_barrier
	s_add_i32 s76, s76, 2
	s_add_u32 s51, s51, 0x100
	s_addc_u32 s75, s75, 0
	s_cmp_gt_u32 s76, 13
	s_mov_b64 s[48:49], s[52:53]

.LBB0_564:
	s_ashr_i32 s77, s76, 31
	s_lshl_b64 s[50:51], s[76:77], 19
	s_add_u32 s82, s49, s50
	s_addc_u32 s83, s53, s51
	s_and_b64 s[0:1], s[0:1], exec
	s_cselect_b32 s13, s83, s89
	s_cselect_b32 s77, s82, s88
	v_lshl_add_u64 v[92:93], s[84:85], 0, v[168:169]
	s_add_u32 vcc_lo, s88, 0x100
	v_lshl_add_u64 v[130:131], v[92:93], 0, s[86:87]
	s_addc_u32 vcc_hi, s89, 0
	s_mov_b32 s50, -2
	s_mov_b64 s[0:1], 0
	s_waitcnt vmcnt(0)
	ds_read_b128 v[132:135], v207
	ds_read_b128 v[136:139], v207 offset:1024
	ds_read_b128 v[140:143], v207 offset:2048
	ds_read_b128 v[144:147], v207 offset:3072
	ds_read_b128 v[148:151], v208
	ds_read_b128 v[152:155], v208 offset:1024
	ds_read_b128 v[156:159], v208 offset:2048
	ds_read_b128 v[174:177], v208 offset:3072
	s_add_u32 s51, s84, s0
	s_addc_u32 s68, s85, s1
	s_add_u32 s51, s51, 0x100
	s_addc_u32 s68, s68, 0
	s_add_u32 s69, vcc_lo, s0
	s_addc_u32 s70, vcc_hi, s1
	s_cmpk_eq_i32 s0, 0x700
	s_cselect_b32 s91, s79, s68
	s_cselect_b32 s90, s78, s51
	s_cselect_b32 s51, s81, s87
	s_cselect_b32 s71, s80, s86
	s_cselect_b32 s89, s13, s70
	s_cselect_b32 s88, s77, s69
	v_lshl_add_u64 v[160:161], v[92:93], 0, s[0:1]
	s_add_i32 m0, s59, 0xc000
	ds_read_b128 v[194:197], v209
	ds_read_b128 v[198:201], v209 offset:1024
	ds_read_b128 v[212:215], v209 offset:2048
	ds_read_b128 v[224:227], v209 offset:3072
	ds_read_b128 v[228:231], v209 offset:4096
	ds_read_b128 v[232:235], v209 offset:5120
	ds_read_b128 v[236:239], v209 offset:6144
	ds_read_b128 v[240:243], v209 offset:7168
	global_load_lds_dwordx4 v[160:161], off
	v_lshl_add_u64 v[160:161], v[130:131], 0, s[0:1]
	s_add_i32 m0, s59, 0xe000
	s_nop 0
	global_load_lds_dwordx4 v[160:161], off
	s_waitcnt vmcnt(8)
	s_waitcnt lgkmcnt(0)
	s_barrier
	s_setprio 1
	s_waitcnt lgkmcnt(0)
	v_mfma_f32_16x16x32_bf16 v[126:129], v[132:135], v[194:197], 0
	v_mfma_f32_16x16x32_bf16 v[60:63], v[140:143], v[194:197], 0
	v_mfma_f32_16x16x32_bf16 v[118:121], v[132:135], v[212:215], 0
	v_mfma_f32_16x16x32_bf16 v[52:55], v[140:143], v[212:215], 0
	v_mfma_f32_16x16x32_bf16 v[110:113], v[132:135], v[228:231], 0
	v_mfma_f32_16x16x32_bf16 v[44:47], v[140:143], v[228:231], 0
	v_mfma_f32_16x16x32_bf16 v[94:97], v[132:135], v[236:239], 0
	v_mfma_f32_16x16x32_bf16 v[28:31], v[140:143], v[236:239], 0
	v_mfma_f32_16x16x32_bf16 v[126:129], v[136:139], v[198:201], v[126:129]
	v_mfma_f32_16x16x32_bf16 v[60:63], v[144:147], v[198:201], v[60:63]
	v_mfma_f32_16x16x32_bf16 v[118:121], v[136:139], v[224:227], v[118:121]
	v_mfma_f32_16x16x32_bf16 v[52:55], v[144:147], v[224:227], v[52:55]
	v_mfma_f32_16x16x32_bf16 v[110:113], v[136:139], v[232:235], v[110:113]
	v_mfma_f32_16x16x32_bf16 v[44:47], v[144:147], v[232:235], v[44:47]
	v_mfma_f32_16x16x32_bf16 v[94:97], v[136:139], v[240:243], v[94:97]
	v_mfma_f32_16x16x32_bf16 v[28:31], v[144:147], v[240:243], v[28:31]
	s_setprio 0
	s_setprio 1
	v_mfma_f32_16x16x32_bf16 v[122:125], v[148:151], v[194:197], 0
	v_mfma_f32_16x16x32_bf16 v[56:59], v[156:159], v[194:197], 0
	v_mfma_f32_16x16x32_bf16 v[114:117], v[148:151], v[212:215], 0
	v_mfma_f32_16x16x32_bf16 v[48:51], v[156:159], v[212:215], 0
	v_mfma_f32_16x16x32_bf16 v[102:105], v[148:151], v[228:231], 0
	v_mfma_f32_16x16x32_bf16 v[36:39], v[156:159], v[228:231], 0
	v_mfma_f32_16x16x32_bf16 v[88:91], v[148:151], v[236:239], 0
	v_mfma_f32_16x16x32_bf16 v[24:27], v[156:159], v[236:239], 0
	v_mfma_f32_16x16x32_bf16 v[122:125], v[152:155], v[198:201], v[122:125]
	v_mfma_f32_16x16x32_bf16 v[56:59], v[174:177], v[198:201], v[56:59]
	v_mfma_f32_16x16x32_bf16 v[114:117], v[152:155], v[224:227], v[114:117]
	v_mfma_f32_16x16x32_bf16 v[48:51], v[174:177], v[224:227], v[48:51]
	v_mfma_f32_16x16x32_bf16 v[102:105], v[152:155], v[232:235], v[102:105]
	v_mfma_f32_16x16x32_bf16 v[36:39], v[174:177], v[232:235], v[36:39]
	v_mfma_f32_16x16x32_bf16 v[88:91], v[152:155], v[240:243], v[88:91]
	v_mfma_f32_16x16x32_bf16 v[24:27], v[174:177], v[240:243], v[24:27]
	s_setprio 0
	s_barrier
	s_add_i32 s68, s95, s57
	v_lshl_add_u64 v[160:161], s[88:89], 0, v[164:165]
	s_mov_b32 m0, s68
	ds_read_b128 v[194:197], v209 offset:16384
	ds_read_b128 v[198:201], v209 offset:17408
	ds_read_b128 v[212:215], v209 offset:18432
	ds_read_b128 v[224:227], v209 offset:19456
	ds_read_b128 v[228:231], v209 offset:20480
	ds_read_b128 v[232:235], v209 offset:21504
	ds_read_b128 v[236:239], v209 offset:22528
	ds_read_b128 v[240:243], v209 offset:23552
	global_load_lds_dwordx4 v[160:161], off
	s_add_i32 m0, s68, 0x2000
	s_add_u32 s68, s88, 0x40000
	v_lshl_add_u64 v[216:217], s[88:89], 0, v[166:167]
	s_addc_u32 s69, s89, 0
	s_add_i32 s70, s96, s57
	global_load_lds_dwordx4 v[216:217], off
	v_lshl_add_u64 v[220:221], s[68:69], 0, v[164:165]
	s_mov_b32 m0, s70
	s_nop 0
	global_load_lds_dwordx4 v[220:221], off
	s_add_i32 m0, s70, 0x2000
	v_lshl_add_u64 v[220:221], s[68:69], 0, v[166:167]
	s_add_u32 s68, s90, s71
	global_load_lds_dwordx4 v[220:221], off
	v_lshl_add_u64 v[220:221], s[90:91], 0, v[162:163]
	s_mov_b32 m0, s59
	s_addc_u32 s69, s91, s51
	global_load_lds_dwordx4 v[220:221], off
	v_lshl_add_u64 v[244:245], s[68:69], 0, v[162:163]
	s_mov_b32 m0, s61
	s_nop 0
	global_load_lds_dwordx4 v[244:245], off
	s_waitcnt vmcnt(8)
	s_waitcnt lgkmcnt(0)
	s_barrier
	s_setprio 1
	s_waitcnt lgkmcnt(0)
	v_mfma_f32_16x16x32_bf16 v[84:87], v[132:135], v[194:197], 0
	v_mfma_f32_16x16x32_bf16 v[20:23], v[140:143], v[194:197], 0
	v_mfma_f32_16x16x32_bf16 v[76:79], v[132:135], v[212:215], 0
	v_mfma_f32_16x16x32_bf16 v[12:15], v[140:143], v[212:215], 0
	v_mfma_f32_16x16x32_bf16 v[68:71], v[132:135], v[228:231], 0
	v_mfma_f32_16x16x32_bf16 v[4:7], v[140:143], v[228:231], 0
	v_mfma_f32_16x16x32_bf16 v[106:109], v[132:135], v[236:239], 0
	v_mfma_f32_16x16x32_bf16 v[40:43], v[140:143], v[236:239], 0
	v_mfma_f32_16x16x32_bf16 v[84:87], v[136:139], v[198:201], v[84:87]
	v_mfma_f32_16x16x32_bf16 v[20:23], v[144:147], v[198:201], v[20:23]
	v_mfma_f32_16x16x32_bf16 v[76:79], v[136:139], v[224:227], v[76:79]
	v_mfma_f32_16x16x32_bf16 v[12:15], v[144:147], v[224:227], v[12:15]
	v_mfma_f32_16x16x32_bf16 v[68:71], v[136:139], v[232:235], v[68:71]
	v_mfma_f32_16x16x32_bf16 v[4:7], v[144:147], v[232:235], v[4:7]
	v_mfma_f32_16x16x32_bf16 v[106:109], v[136:139], v[240:243], v[106:109]
	v_mfma_f32_16x16x32_bf16 v[40:43], v[144:147], v[240:243], v[40:43]
	s_setprio 0
	s_setprio 1
	v_mfma_f32_16x16x32_bf16 v[80:83], v[148:151], v[194:197], 0
	v_mfma_f32_16x16x32_bf16 v[16:19], v[156:159], v[194:197], 0
	v_mfma_f32_16x16x32_bf16 v[72:75], v[148:151], v[212:215], 0
	v_mfma_f32_16x16x32_bf16 v[8:11], v[156:159], v[212:215], 0
	v_mfma_f32_16x16x32_bf16 v[64:67], v[148:151], v[228:231], 0
	v_mfma_f32_16x16x32_bf16 v[0:3], v[156:159], v[228:231], 0
	v_mfma_f32_16x16x32_bf16 v[98:101], v[148:151], v[236:239], 0
	v_mfma_f32_16x16x32_bf16 v[32:35], v[156:159], v[236:239], 0
	v_mfma_f32_16x16x32_bf16 v[80:83], v[152:155], v[198:201], v[80:83]
	v_mfma_f32_16x16x32_bf16 v[16:19], v[174:177], v[198:201], v[16:19]
	v_mfma_f32_16x16x32_bf16 v[72:75], v[152:155], v[224:227], v[72:75]
	v_mfma_f32_16x16x32_bf16 v[8:11], v[174:177], v[224:227], v[8:11]
	v_mfma_f32_16x16x32_bf16 v[64:67], v[152:155], v[232:235], v[64:67]
	v_mfma_f32_16x16x32_bf16 v[0:3], v[174:177], v[232:235], v[0:3]
	v_mfma_f32_16x16x32_bf16 v[98:101], v[152:155], v[240:243], v[98:101]
	v_mfma_f32_16x16x32_bf16 v[32:35], v[174:177], v[240:243], v[32:35]
	s_setprio 0
	s_barrier
	s_add_i32 s70, 0, 0x18000
	s_add_i32 s14, 0, 0x1c000
	v_add_u32_e32 v144, s70, v203
	v_add_u32_e32 v174, s14, v203
	ds_read_b128 v[132:135], v144
	ds_read_b128 v[136:139], v144 offset:1024
	ds_read_b128 v[140:143], v144 offset:2048
	ds_read_b128 v[144:147], v144 offset:3072
	ds_read_b128 v[148:151], v174
	ds_read_b128 v[152:155], v174 offset:1024
	ds_read_b128 v[156:159], v174 offset:2048
	ds_read_b128 v[174:177], v174 offset:3072
	s_add_u32 s68, s90, 0x2000
	s_addc_u32 s69, s91, 0
	v_lshl_add_u64 v[246:247], s[68:69], 0, v[162:163]
	s_add_u32 s68, s68, s71
	s_mov_b32 m0, s63
	s_addc_u32 s69, s69, s51
	ds_read_b128 v[194:197], v209 offset:32768
	ds_read_b128 v[198:201], v209 offset:33792
	ds_read_b128 v[212:215], v209 offset:34816
	ds_read_b128 v[224:227], v209 offset:35840
	ds_read_b128 v[228:231], v209 offset:36864
	ds_read_b128 v[232:235], v209 offset:37888
	ds_read_b128 v[236:239], v209 offset:38912
	ds_read_b128 v[240:243], v209 offset:39936
	global_load_lds_dwordx4 v[246:247], off
	v_lshl_add_u64 v[246:247], s[68:69], 0, v[162:163]
	s_mov_b32 m0, s67
	s_nop 0
	global_load_lds_dwordx4 v[246:247], off
	s_waitcnt vmcnt(8)
	s_waitcnt lgkmcnt(0)
	s_barrier
	s_setprio 1
	s_waitcnt lgkmcnt(0)
	v_mfma_f32_16x16x32_bf16 v[126:129], v[132:135], v[194:197], v[126:129]
	v_mfma_f32_16x16x32_bf16 v[60:63], v[140:143], v[194:197], v[60:63]
	v_mfma_f32_16x16x32_bf16 v[118:121], v[132:135], v[212:215], v[118:121]
	v_mfma_f32_16x16x32_bf16 v[52:55], v[140:143], v[212:215], v[52:55]
	v_mfma_f32_16x16x32_bf16 v[110:113], v[132:135], v[228:231], v[110:113]
	v_mfma_f32_16x16x32_bf16 v[44:47], v[140:143], v[228:231], v[44:47]
	v_mfma_f32_16x16x32_bf16 v[94:97], v[132:135], v[236:239], v[94:97]
	v_mfma_f32_16x16x32_bf16 v[28:31], v[140:143], v[236:239], v[28:31]
	v_mfma_f32_16x16x32_bf16 v[126:129], v[136:139], v[198:201], v[126:129]
	v_mfma_f32_16x16x32_bf16 v[60:63], v[144:147], v[198:201], v[60:63]
	v_mfma_f32_16x16x32_bf16 v[118:121], v[136:139], v[224:227], v[118:121]
	v_mfma_f32_16x16x32_bf16 v[52:55], v[144:147], v[224:227], v[52:55]
	v_mfma_f32_16x16x32_bf16 v[110:113], v[136:139], v[232:235], v[110:113]
	v_mfma_f32_16x16x32_bf16 v[44:47], v[144:147], v[232:235], v[44:47]
	v_mfma_f32_16x16x32_bf16 v[94:97], v[136:139], v[240:243], v[94:97]
	v_mfma_f32_16x16x32_bf16 v[28:31], v[144:147], v[240:243], v[28:31]
	s_setprio 0
	s_setprio 1
	v_mfma_f32_16x16x32_bf16 v[122:125], v[148:151], v[194:197], v[122:125]
	v_mfma_f32_16x16x32_bf16 v[56:59], v[156:159], v[194:197], v[56:59]
	v_mfma_f32_16x16x32_bf16 v[114:117], v[148:151], v[212:215], v[114:117]
	v_mfma_f32_16x16x32_bf16 v[48:51], v[156:159], v[212:215], v[48:51]
	v_mfma_f32_16x16x32_bf16 v[102:105], v[148:151], v[228:231], v[102:105]
	v_mfma_f32_16x16x32_bf16 v[36:39], v[156:159], v[228:231], v[36:39]
	v_mfma_f32_16x16x32_bf16 v[88:91], v[148:151], v[236:239], v[88:91]
	v_mfma_f32_16x16x32_bf16 v[24:27], v[156:159], v[236:239], v[24:27]
	v_mfma_f32_16x16x32_bf16 v[122:125], v[152:155], v[198:201], v[122:125]
	v_mfma_f32_16x16x32_bf16 v[56:59], v[174:177], v[198:201], v[56:59]
	v_mfma_f32_16x16x32_bf16 v[114:117], v[152:155], v[224:227], v[114:117]
	v_mfma_f32_16x16x32_bf16 v[48:51], v[174:177], v[224:227], v[48:51]
	v_mfma_f32_16x16x32_bf16 v[102:105], v[152:155], v[232:235], v[102:105]
	v_mfma_f32_16x16x32_bf16 v[36:39], v[174:177], v[232:235], v[36:39]
	v_mfma_f32_16x16x32_bf16 v[88:91], v[152:155], v[240:243], v[88:91]
	v_mfma_f32_16x16x32_bf16 v[24:27], v[174:177], v[240:243], v[24:27]
	s_setprio 0
	s_barrier
	s_add_i32 s15, s70, s57
	v_lshl_add_u64 v[160:161], v[160:161], 0, s[22:23]
	s_mov_b32 m0, s15
	ds_read_b128 v[194:197], v209 offset:49152
	ds_read_b128 v[198:201], v209 offset:50176
	ds_read_b128 v[212:215], v209 offset:51200
	ds_read_b128 v[224:227], v209 offset:52224
	ds_read_b128 v[228:231], v209 offset:53248
	ds_read_b128 v[232:235], v209 offset:54272
	ds_read_b128 v[236:239], v209 offset:55296
	ds_read_b128 v[240:243], v209 offset:56320
	global_load_lds_dwordx4 v[160:161], off
	s_add_i32 m0, s15, 0x2000
	s_add_u32 s68, s88, 0x40080
	v_lshl_add_u64 v[160:161], v[216:217], 0, s[22:23]
	s_addc_u32 s69, s89, 0
	s_add_i32 s14, s14, s57
	global_load_lds_dwordx4 v[160:161], off
	v_lshl_add_u64 v[160:161], s[68:69], 0, v[164:165]
	s_mov_b32 m0, s14
	s_nop 0
	global_load_lds_dwordx4 v[160:161], off
	v_lshl_add_u64 v[160:161], s[68:69], 0, v[166:167]
	s_add_i32 m0, s14, 0x2000
	s_nop 0
	global_load_lds_dwordx4 v[160:161], off
	v_lshl_add_u64 v[160:161], v[220:221], 0, s[22:23]
	s_mov_b32 m0, s75
	s_nop 0
	global_load_lds_dwordx4 v[160:161], off
	v_lshl_add_u64 v[160:161], v[244:245], 0, s[22:23]
	s_mov_b32 m0, s92
	s_nop 0
	global_load_lds_dwordx4 v[160:161], off
	s_waitcnt vmcnt(8)
	s_waitcnt lgkmcnt(0)
	s_barrier
	s_setprio 1
	s_waitcnt lgkmcnt(0)
	v_mfma_f32_16x16x32_bf16 v[84:87], v[132:135], v[194:197], v[84:87]
	v_mfma_f32_16x16x32_bf16 v[20:23], v[140:143], v[194:197], v[20:23]
	v_mfma_f32_16x16x32_bf16 v[76:79], v[132:135], v[212:215], v[76:79]
	v_mfma_f32_16x16x32_bf16 v[12:15], v[140:143], v[212:215], v[12:15]
	v_mfma_f32_16x16x32_bf16 v[68:71], v[132:135], v[228:231], v[68:71]
	v_mfma_f32_16x16x32_bf16 v[4:7], v[140:143], v[228:231], v[4:7]
	v_mfma_f32_16x16x32_bf16 v[106:109], v[132:135], v[236:239], v[106:109]
	v_mfma_f32_16x16x32_bf16 v[40:43], v[140:143], v[236:239], v[40:43]
	v_mfma_f32_16x16x32_bf16 v[84:87], v[136:139], v[198:201], v[84:87]
	v_mfma_f32_16x16x32_bf16 v[20:23], v[144:147], v[198:201], v[20:23]
	v_mfma_f32_16x16x32_bf16 v[76:79], v[136:139], v[224:227], v[76:79]
	v_mfma_f32_16x16x32_bf16 v[12:15], v[144:147], v[224:227], v[12:15]
	v_mfma_f32_16x16x32_bf16 v[68:71], v[136:139], v[232:235], v[68:71]
	v_mfma_f32_16x16x32_bf16 v[4:7], v[144:147], v[232:235], v[4:7]
	v_mfma_f32_16x16x32_bf16 v[106:109], v[136:139], v[240:243], v[106:109]
	v_mfma_f32_16x16x32_bf16 v[40:43], v[144:147], v[240:243], v[40:43]
	s_setprio 0
	s_setprio 1
	v_mfma_f32_16x16x32_bf16 v[80:83], v[148:151], v[194:197], v[80:83]
	v_mfma_f32_16x16x32_bf16 v[16:19], v[156:159], v[194:197], v[16:19]
	v_mfma_f32_16x16x32_bf16 v[72:75], v[148:151], v[212:215], v[72:75]
	v_mfma_f32_16x16x32_bf16 v[8:11], v[156:159], v[212:215], v[8:11]
	v_mfma_f32_16x16x32_bf16 v[64:67], v[148:151], v[228:231], v[64:67]
	v_mfma_f32_16x16x32_bf16 v[0:3], v[156:159], v[228:231], v[0:3]
	v_mfma_f32_16x16x32_bf16 v[98:101], v[148:151], v[236:239], v[98:101]
	v_mfma_f32_16x16x32_bf16 v[32:35], v[156:159], v[236:239], v[32:35]
	v_mfma_f32_16x16x32_bf16 v[80:83], v[152:155], v[198:201], v[80:83]
	v_mfma_f32_16x16x32_bf16 v[16:19], v[174:177], v[198:201], v[16:19]
	v_mfma_f32_16x16x32_bf16 v[72:75], v[152:155], v[224:227], v[72:75]
	v_mfma_f32_16x16x32_bf16 v[8:11], v[174:177], v[224:227], v[8:11]
	v_mfma_f32_16x16x32_bf16 v[64:67], v[152:155], v[232:235], v[64:67]
	v_mfma_f32_16x16x32_bf16 v[0:3], v[174:177], v[232:235], v[0:3]
	v_mfma_f32_16x16x32_bf16 v[98:101], v[152:155], v[240:243], v[98:101]
	v_mfma_f32_16x16x32_bf16 v[32:35], v[174:177], v[240:243], v[32:35]
	s_setprio 0
	s_barrier
	s_add_i32 s50, s50, 2
	s_add_u32 s0, s0, 0x100
	s_addc_u32 s1, s1, 0
	s_cmp_gt_u32 s50, 13

.LBB0_661:
	s_add_u32 s64, s44, 0x100
	s_addc_u32 s65, s45, 0
	s_mov_b32 s66, -2
	s_waitcnt lgkmcnt(0)
	s_waitcnt vmcnt(0)
	ds_read_b128 v[144:147], v151
	ds_read_b128 v[156:159], v151 offset:1024
	ds_read_b128 v[160:163], v151 offset:2048
	ds_read_b128 v[164:167], v151 offset:3072
	ds_read_b128 v[168:171], v152
	ds_read_b128 v[172:175], v152 offset:1024
	ds_read_b128 v[176:179], v152 offset:2048
	ds_read_b128 v[180:183], v152 offset:3072
	s_add_u32 s44, s42, 0x100
	s_addc_u32 s45, s43, 0
	s_cmp_eq_u32 s66, 40
	s_cselect_b32 s69, s1, s45
	s_cselect_b32 s68, s0, s44
	s_cselect_b32 s47, s41, s65
	s_cselect_b32 s46, s40, s64
	v_lshl_add_u64 v[216:217], s[42:43], 0, v[136:137]
	s_add_i32 m0, s48, 0xc000
	ds_read_b128 v[184:187], v153
	ds_read_b128 v[188:191], v153 offset:1024
	ds_read_b128 v[192:195], v153 offset:2048
	ds_read_b128 v[196:199], v153 offset:3072
	ds_read_b128 v[200:203], v153 offset:4096
	ds_read_b128 v[204:207], v153 offset:5120
	ds_read_b128 v[208:211], v153 offset:6144
	ds_read_b128 v[212:215], v153 offset:7168
	global_load_lds_dwordx4 v[216:217], off
	v_lshl_add_u64 v[216:217], s[42:43], 0, v[138:139]
	s_add_i32 m0, s48, 0xe000
	s_nop 0
	global_load_lds_dwordx4 v[216:217], off
	s_waitcnt vmcnt(8)
	s_waitcnt lgkmcnt(0)
	s_barrier
	s_setprio 1
	s_waitcnt lgkmcnt(0)
	v_mfma_f32_16x16x32_bf16 v[124:127], v[144:147], v[184:187], 0
	v_mfma_f32_16x16x32_bf16 v[120:123], v[160:163], v[184:187], 0
	v_mfma_f32_16x16x32_bf16 v[108:111], v[144:147], v[192:195], 0
	v_mfma_f32_16x16x32_bf16 v[104:107], v[160:163], v[192:195], 0
	v_mfma_f32_16x16x32_bf16 v[92:95], v[144:147], v[200:203], 0
	v_mfma_f32_16x16x32_bf16 v[88:91], v[160:163], v[200:203], 0
	v_mfma_f32_16x16x32_bf16 v[76:79], v[144:147], v[208:211], 0
	v_mfma_f32_16x16x32_bf16 v[72:75], v[160:163], v[208:211], 0
	v_mfma_f32_16x16x32_bf16 v[124:127], v[156:159], v[188:191], v[124:127]
	v_mfma_f32_16x16x32_bf16 v[120:123], v[164:167], v[188:191], v[120:123]
	v_mfma_f32_16x16x32_bf16 v[108:111], v[156:159], v[196:199], v[108:111]
	v_mfma_f32_16x16x32_bf16 v[104:107], v[164:167], v[196:199], v[104:107]
	v_mfma_f32_16x16x32_bf16 v[92:95], v[156:159], v[204:207], v[92:95]
	v_mfma_f32_16x16x32_bf16 v[88:91], v[164:167], v[204:207], v[88:91]
	v_mfma_f32_16x16x32_bf16 v[76:79], v[156:159], v[212:215], v[76:79]
	v_mfma_f32_16x16x32_bf16 v[72:75], v[164:167], v[212:215], v[72:75]
	s_setprio 0
	s_setprio 1
	v_mfma_f32_16x16x32_bf16 v[116:119], v[168:171], v[184:187], 0
	v_mfma_f32_16x16x32_bf16 v[112:115], v[176:179], v[184:187], 0
	v_mfma_f32_16x16x32_bf16 v[100:103], v[168:171], v[192:195], 0
	v_mfma_f32_16x16x32_bf16 v[96:99], v[176:179], v[192:195], 0
	v_mfma_f32_16x16x32_bf16 v[84:87], v[168:171], v[200:203], 0
	v_mfma_f32_16x16x32_bf16 v[80:83], v[176:179], v[200:203], 0
	v_mfma_f32_16x16x32_bf16 v[68:71], v[168:171], v[208:211], 0
	v_mfma_f32_16x16x32_bf16 v[64:67], v[176:179], v[208:211], 0
	v_mfma_f32_16x16x32_bf16 v[116:119], v[172:175], v[188:191], v[116:119]
	v_mfma_f32_16x16x32_bf16 v[112:115], v[180:183], v[188:191], v[112:115]
	v_mfma_f32_16x16x32_bf16 v[100:103], v[172:175], v[196:199], v[100:103]
	v_mfma_f32_16x16x32_bf16 v[96:99], v[180:183], v[196:199], v[96:99]
	v_mfma_f32_16x16x32_bf16 v[84:87], v[172:175], v[204:207], v[84:87]
	v_mfma_f32_16x16x32_bf16 v[80:83], v[180:183], v[204:207], v[80:83]
	v_mfma_f32_16x16x32_bf16 v[68:71], v[172:175], v[212:215], v[68:71]
	v_mfma_f32_16x16x32_bf16 v[64:67], v[180:183], v[212:215], v[64:67]
	s_setprio 0
	s_barrier
	s_add_i32 s42, s59, s35
	v_lshl_add_u64 v[216:217], s[46:47], 0, v[130:131]
	s_mov_b32 m0, s42
	ds_read_b128 v[184:187], v153 offset:16384
	ds_read_b128 v[188:191], v153 offset:17408
	ds_read_b128 v[192:195], v153 offset:18432
	ds_read_b128 v[196:199], v153 offset:19456
	ds_read_b128 v[200:203], v153 offset:20480
	ds_read_b128 v[204:207], v153 offset:21504
	ds_read_b128 v[208:211], v153 offset:22528
	ds_read_b128 v[212:215], v153 offset:23552
	global_load_lds_dwordx4 v[216:217], off
	s_add_i32 m0, s42, 0x2000
	s_add_u32 s42, s46, 0xb0000
	v_lshl_add_u64 v[220:221], s[46:47], 0, v[134:135]
	s_addc_u32 s43, s47, 0
	s_add_i32 s67, s60, s35
	global_load_lds_dwordx4 v[220:221], off
	v_lshl_add_u64 v[224:225], s[42:43], 0, v[130:131]
	s_mov_b32 m0, s67
	v_lshl_add_u64 v[226:227], s[68:69], 0, v[132:133]
	global_load_lds_dwordx4 v[224:225], off
	v_lshl_add_u64 v[224:225], s[42:43], 0, v[134:135]
	s_add_i32 m0, s67, 0x2000
	v_lshl_add_u64 v[228:229], v[226:227], 0, s[14:15]
	global_load_lds_dwordx4 v[224:225], off
	v_lshl_add_u64 v[224:225], s[68:69], 0, v[128:129]
	s_mov_b32 m0, s48
	s_nop 0
	global_load_lds_dwordx4 v[224:225], off
	s_mov_b32 m0, s49
	s_nop 0
	global_load_lds_dwordx4 v[228:229], off
	s_waitcnt vmcnt(8)
	s_waitcnt lgkmcnt(0)
	s_barrier
	s_setprio 1
	s_waitcnt lgkmcnt(0)
	v_mfma_f32_16x16x32_bf16 v[60:63], v[144:147], v[184:187], 0
	v_mfma_f32_16x16x32_bf16 v[56:59], v[160:163], v[184:187], 0
	v_mfma_f32_16x16x32_bf16 v[44:47], v[144:147], v[192:195], 0
	v_mfma_f32_16x16x32_bf16 v[40:43], v[160:163], v[192:195], 0
	v_mfma_f32_16x16x32_bf16 v[28:31], v[144:147], v[200:203], 0
	v_mfma_f32_16x16x32_bf16 v[24:27], v[160:163], v[200:203], 0
	v_mfma_f32_16x16x32_bf16 v[12:15], v[144:147], v[208:211], 0
	v_mfma_f32_16x16x32_bf16 v[8:11], v[160:163], v[208:211], 0
	v_mfma_f32_16x16x32_bf16 v[60:63], v[156:159], v[188:191], v[60:63]
	v_mfma_f32_16x16x32_bf16 v[56:59], v[164:167], v[188:191], v[56:59]
	v_mfma_f32_16x16x32_bf16 v[44:47], v[156:159], v[196:199], v[44:47]
	v_mfma_f32_16x16x32_bf16 v[40:43], v[164:167], v[196:199], v[40:43]
	v_mfma_f32_16x16x32_bf16 v[28:31], v[156:159], v[204:207], v[28:31]
	v_mfma_f32_16x16x32_bf16 v[24:27], v[164:167], v[204:207], v[24:27]
	v_mfma_f32_16x16x32_bf16 v[12:15], v[156:159], v[212:215], v[12:15]
	v_mfma_f32_16x16x32_bf16 v[8:11], v[164:167], v[212:215], v[8:11]
	s_setprio 0
	s_setprio 1
	v_mfma_f32_16x16x32_bf16 v[52:55], v[168:171], v[184:187], 0
	v_mfma_f32_16x16x32_bf16 v[48:51], v[176:179], v[184:187], 0
	v_mfma_f32_16x16x32_bf16 v[36:39], v[168:171], v[192:195], 0
	v_mfma_f32_16x16x32_bf16 v[32:35], v[176:179], v[192:195], 0
	v_mfma_f32_16x16x32_bf16 v[20:23], v[168:171], v[200:203], 0
	v_mfma_f32_16x16x32_bf16 v[16:19], v[176:179], v[200:203], 0
	v_mfma_f32_16x16x32_bf16 v[4:7], v[168:171], v[208:211], 0
	v_mfma_f32_16x16x32_bf16 v[0:3], v[176:179], v[208:211], 0
	v_mfma_f32_16x16x32_bf16 v[52:55], v[172:175], v[188:191], v[52:55]
	v_mfma_f32_16x16x32_bf16 v[48:51], v[180:183], v[188:191], v[48:51]
	v_mfma_f32_16x16x32_bf16 v[36:39], v[172:175], v[196:199], v[36:39]
	v_mfma_f32_16x16x32_bf16 v[32:35], v[180:183], v[196:199], v[32:35]
	v_mfma_f32_16x16x32_bf16 v[20:23], v[172:175], v[204:207], v[20:23]
	v_mfma_f32_16x16x32_bf16 v[16:19], v[180:183], v[204:207], v[16:19]
	v_mfma_f32_16x16x32_bf16 v[4:7], v[172:175], v[212:215], v[4:7]
	v_mfma_f32_16x16x32_bf16 v[0:3], v[180:183], v[212:215], v[0:3]
	s_setprio 0
	s_barrier
	s_add_i32 s42, 0, 0x18000
	v_add_u32_e32 v155, s42, v149
	s_add_i32 s67, 0, 0x1c000
	ds_read_b128 v[144:147], v155
	ds_read_b128 v[156:159], v155 offset:1024
	ds_read_b128 v[160:163], v155 offset:2048
	ds_read_b128 v[164:167], v155 offset:3072
	v_add_u32_e32 v155, s67, v149
	ds_read_b128 v[168:171], v155
	ds_read_b128 v[172:175], v155 offset:1024
	ds_read_b128 v[176:179], v155 offset:2048
	ds_read_b128 v[180:183], v155 offset:3072
	s_mov_b32 m0, s50
	v_lshl_add_u64 v[228:229], v[224:225], 0, s[12:13]
	ds_read_b128 v[184:187], v153 offset:32768
	ds_read_b128 v[188:191], v153 offset:33792
	ds_read_b128 v[192:195], v153 offset:34816
	ds_read_b128 v[196:199], v153 offset:35840
	ds_read_b128 v[200:203], v153 offset:36864
	ds_read_b128 v[204:207], v153 offset:37888
	ds_read_b128 v[208:211], v153 offset:38912
	ds_read_b128 v[212:215], v153 offset:39936
	global_load_lds_dwordx4 v[228:229], off
	v_lshl_add_u64 v[228:229], v[226:227], 0, s[16:17]
	s_mov_b32 m0, s51
	s_nop 0
	global_load_lds_dwordx4 v[228:229], off
	s_waitcnt vmcnt(8)
	s_waitcnt lgkmcnt(0)
	s_barrier
	s_setprio 1
	s_waitcnt lgkmcnt(0)
	v_mfma_f32_16x16x32_bf16 v[124:127], v[144:147], v[184:187], v[124:127]
	v_mfma_f32_16x16x32_bf16 v[120:123], v[160:163], v[184:187], v[120:123]
	v_mfma_f32_16x16x32_bf16 v[108:111], v[144:147], v[192:195], v[108:111]
	v_mfma_f32_16x16x32_bf16 v[104:107], v[160:163], v[192:195], v[104:107]
	v_mfma_f32_16x16x32_bf16 v[92:95], v[144:147], v[200:203], v[92:95]
	v_mfma_f32_16x16x32_bf16 v[88:91], v[160:163], v[200:203], v[88:91]
	v_mfma_f32_16x16x32_bf16 v[76:79], v[144:147], v[208:211], v[76:79]
	v_mfma_f32_16x16x32_bf16 v[72:75], v[160:163], v[208:211], v[72:75]
	v_mfma_f32_16x16x32_bf16 v[124:127], v[156:159], v[188:191], v[124:127]
	v_mfma_f32_16x16x32_bf16 v[120:123], v[164:167], v[188:191], v[120:123]
	v_mfma_f32_16x16x32_bf16 v[108:111], v[156:159], v[196:199], v[108:111]
	v_mfma_f32_16x16x32_bf16 v[104:107], v[164:167], v[196:199], v[104:107]
	v_mfma_f32_16x16x32_bf16 v[92:95], v[156:159], v[204:207], v[92:95]
	v_mfma_f32_16x16x32_bf16 v[88:91], v[164:167], v[204:207], v[88:91]
	v_mfma_f32_16x16x32_bf16 v[76:79], v[156:159], v[212:215], v[76:79]
	v_mfma_f32_16x16x32_bf16 v[72:75], v[164:167], v[212:215], v[72:75]
	s_setprio 0
	s_setprio 1
	v_mfma_f32_16x16x32_bf16 v[116:119], v[168:171], v[184:187], v[116:119]
	v_mfma_f32_16x16x32_bf16 v[112:115], v[176:179], v[184:187], v[112:115]
	v_mfma_f32_16x16x32_bf16 v[100:103], v[168:171], v[192:195], v[100:103]
	v_mfma_f32_16x16x32_bf16 v[96:99], v[176:179], v[192:195], v[96:99]
	v_mfma_f32_16x16x32_bf16 v[84:87], v[168:171], v[200:203], v[84:87]
	v_mfma_f32_16x16x32_bf16 v[80:83], v[176:179], v[200:203], v[80:83]
	v_mfma_f32_16x16x32_bf16 v[68:71], v[168:171], v[208:211], v[68:71]
	v_mfma_f32_16x16x32_bf16 v[64:67], v[176:179], v[208:211], v[64:67]
	v_mfma_f32_16x16x32_bf16 v[116:119], v[172:175], v[188:191], v[116:119]
	v_mfma_f32_16x16x32_bf16 v[112:115], v[180:183], v[188:191], v[112:115]
	v_mfma_f32_16x16x32_bf16 v[100:103], v[172:175], v[196:199], v[100:103]
	v_mfma_f32_16x16x32_bf16 v[96:99], v[180:183], v[196:199], v[96:99]
	v_mfma_f32_16x16x32_bf16 v[84:87], v[172:175], v[204:207], v[84:87]
	v_mfma_f32_16x16x32_bf16 v[80:83], v[180:183], v[204:207], v[80:83]
	v_mfma_f32_16x16x32_bf16 v[68:71], v[172:175], v[212:215], v[68:71]
	v_mfma_f32_16x16x32_bf16 v[64:67], v[180:183], v[212:215], v[64:67]
	s_setprio 0
	s_barrier
	s_add_i32 s42, s42, s35
	v_lshl_add_u64 v[216:217], v[216:217], 0, s[24:25]
	s_mov_b32 m0, s42
	ds_read_b128 v[184:187], v153 offset:49152
	ds_read_b128 v[188:191], v153 offset:50176
	ds_read_b128 v[192:195], v153 offset:51200
	ds_read_b128 v[196:199], v153 offset:52224
	ds_read_b128 v[200:203], v153 offset:53248
	ds_read_b128 v[204:207], v153 offset:54272
	ds_read_b128 v[208:211], v153 offset:55296
	ds_read_b128 v[212:215], v153 offset:56320
	global_load_lds_dwordx4 v[216:217], off
	s_add_i32 m0, s42, 0x2000
	s_add_u32 s42, s46, 0xb0080
	v_lshl_add_u64 v[216:217], v[220:221], 0, s[24:25]
	s_addc_u32 s43, s47, 0
	s_add_i32 s46, s67, s35
	global_load_lds_dwordx4 v[216:217], off
	v_lshl_add_u64 v[216:217], s[42:43], 0, v[130:131]
	s_mov_b32 m0, s46
	s_nop 0
	global_load_lds_dwordx4 v[216:217], off
	v_lshl_add_u64 v[216:217], s[42:43], 0, v[134:135]
	s_add_i32 m0, s46, 0x2000
	s_nop 0
	global_load_lds_dwordx4 v[216:217], off
	v_lshl_add_u64 v[216:217], v[224:225], 0, s[24:25]
	s_mov_b32 m0, s53
	s_nop 0
	global_load_lds_dwordx4 v[216:217], off
	v_lshl_add_u64 v[216:217], v[226:227], 0, s[36:37]
	s_mov_b32 m0, s54
	s_nop 0
	global_load_lds_dwordx4 v[216:217], off
	s_waitcnt vmcnt(8)
	s_waitcnt lgkmcnt(0)
	s_barrier
	s_setprio 1
	s_waitcnt lgkmcnt(0)
	v_mfma_f32_16x16x32_bf16 v[60:63], v[144:147], v[184:187], v[60:63]
	v_mfma_f32_16x16x32_bf16 v[56:59], v[160:163], v[184:187], v[56:59]
	v_mfma_f32_16x16x32_bf16 v[44:47], v[144:147], v[192:195], v[44:47]
	v_mfma_f32_16x16x32_bf16 v[40:43], v[160:163], v[192:195], v[40:43]
	v_mfma_f32_16x16x32_bf16 v[28:31], v[144:147], v[200:203], v[28:31]
	v_mfma_f32_16x16x32_bf16 v[24:27], v[160:163], v[200:203], v[24:27]
	v_mfma_f32_16x16x32_bf16 v[12:15], v[144:147], v[208:211], v[12:15]
	v_mfma_f32_16x16x32_bf16 v[8:11], v[160:163], v[208:211], v[8:11]
	v_mfma_f32_16x16x32_bf16 v[60:63], v[156:159], v[188:191], v[60:63]
	v_mfma_f32_16x16x32_bf16 v[56:59], v[164:167], v[188:191], v[56:59]
	v_mfma_f32_16x16x32_bf16 v[44:47], v[156:159], v[196:199], v[44:47]
	v_mfma_f32_16x16x32_bf16 v[40:43], v[164:167], v[196:199], v[40:43]
	v_mfma_f32_16x16x32_bf16 v[28:31], v[156:159], v[204:207], v[28:31]
	v_mfma_f32_16x16x32_bf16 v[24:27], v[164:167], v[204:207], v[24:27]
	v_mfma_f32_16x16x32_bf16 v[12:15], v[156:159], v[212:215], v[12:15]
	v_mfma_f32_16x16x32_bf16 v[8:11], v[164:167], v[212:215], v[8:11]
	s_setprio 0
	s_setprio 1
	v_mfma_f32_16x16x32_bf16 v[52:55], v[168:171], v[184:187], v[52:55]
	v_mfma_f32_16x16x32_bf16 v[48:51], v[176:179], v[184:187], v[48:51]
	v_mfma_f32_16x16x32_bf16 v[36:39], v[168:171], v[192:195], v[36:39]
	v_mfma_f32_16x16x32_bf16 v[32:35], v[176:179], v[192:195], v[32:35]
	v_mfma_f32_16x16x32_bf16 v[20:23], v[168:171], v[200:203], v[20:23]
	v_mfma_f32_16x16x32_bf16 v[16:19], v[176:179], v[200:203], v[16:19]
	v_mfma_f32_16x16x32_bf16 v[4:7], v[168:171], v[208:211], v[4:7]
	v_mfma_f32_16x16x32_bf16 v[0:3], v[176:179], v[208:211], v[0:3]
	v_mfma_f32_16x16x32_bf16 v[52:55], v[172:175], v[188:191], v[52:55]
	v_mfma_f32_16x16x32_bf16 v[48:51], v[180:183], v[188:191], v[48:51]
	v_mfma_f32_16x16x32_bf16 v[36:39], v[172:175], v[196:199], v[36:39]
	v_mfma_f32_16x16x32_bf16 v[32:35], v[180:183], v[196:199], v[32:35]
	v_mfma_f32_16x16x32_bf16 v[20:23], v[172:175], v[204:207], v[20:23]
	v_mfma_f32_16x16x32_bf16 v[16:19], v[180:183], v[204:207], v[16:19]
	v_mfma_f32_16x16x32_bf16 v[4:7], v[172:175], v[212:215], v[4:7]
	v_mfma_f32_16x16x32_bf16 v[0:3], v[180:183], v[212:215], v[0:3]
	s_setprio 0
	s_barrier
	s_add_i32 s66, s66, 2
	s_add_u32 s64, s64, 0x100
	s_addc_u32 s65, s65, 0
	s_cmp_gt_u32 s66, 41
	s_mov_b64 s[42:43], s[44:45]

.LBB0_750:
	s_lshl_b32 s38, s65, 8
	s_ashr_i32 s39, s38, 31
	s_lshl_b64 s[38:39], s[38:39], 11
	s_add_u32 s38, s8, s38
	s_addc_u32 s39, s9, s39
	s_and_b64 s[40:41], s[4:5], exec
	s_cselect_b32 s43, s39, s45
	s_cselect_b32 s67, s38, s44
	s_ashr_i32 s37, s36, 31
	s_lshl_b64 s[40:41], s[36:37], 19
	s_add_u32 s40, s3, s40
	s_addc_u32 s41, s33, s41
	s_and_b64 s[48:49], s[4:5], exec
	s_cselect_b32 s37, s41, s47
	s_cselect_b32 s68, s40, s46
	s_add_u32 s69, s46, 0x100
	s_addc_u32 s71, s47, 0
	s_mov_b32 s72, -2
	s_waitcnt vmcnt(0)
	ds_read_b128 v[144:147], v189
	ds_read_b128 v[148:151], v189 offset:1024
	ds_read_b128 v[152:155], v189 offset:2048
	ds_read_b128 v[156:159], v189 offset:3072
	ds_read_b128 v[160:163], v190
	ds_read_b128 v[164:167], v190 offset:1024
	ds_read_b128 v[168:171], v190 offset:2048
	ds_read_b128 v[172:175], v190 offset:3072
	s_add_u32 s46, s44, 0x100
	s_addc_u32 s47, s45, 0
	s_cmp_eq_u32 s72, 12
	s_cselect_b32 s75, s43, s47
	s_cselect_b32 s74, s67, s46
	s_cselect_b32 s49, s37, s71
	s_cselect_b32 s48, s68, s69
	v_lshl_add_u64 v[184:185], s[44:45], 0, v[136:137]
	s_add_i32 m0, s51, 0xc000
	ds_read_b128 v[176:179], v191
	ds_read_b128 v[180:183], v191 offset:1024
	ds_read_b128 v[194:197], v191 offset:2048
	ds_read_b128 v[198:201], v191 offset:3072
	ds_read_b128 v[202:205], v191 offset:4096
	ds_read_b128 v[206:209], v191 offset:5120
	ds_read_b128 v[210:213], v191 offset:6144
	ds_read_b128 v[214:217], v191 offset:7168
	global_load_lds_dwordx4 v[184:185], off
	v_lshl_add_u64 v[184:185], s[44:45], 0, v[138:139]
	s_add_i32 m0, s51, 0xe000
	s_nop 0
	global_load_lds_dwordx4 v[184:185], off
	s_waitcnt vmcnt(8)
	s_waitcnt lgkmcnt(0)
	s_barrier
	s_setprio 1
	s_waitcnt lgkmcnt(0)
	v_mfma_f32_16x16x32_bf16 v[124:127], v[144:147], v[176:179], 0
	v_mfma_f32_16x16x32_bf16 v[120:123], v[152:155], v[176:179], 0
	v_mfma_f32_16x16x32_bf16 v[108:111], v[144:147], v[194:197], 0
	v_mfma_f32_16x16x32_bf16 v[104:107], v[152:155], v[194:197], 0
	v_mfma_f32_16x16x32_bf16 v[92:95], v[144:147], v[202:205], 0
	v_mfma_f32_16x16x32_bf16 v[88:91], v[152:155], v[202:205], 0
	v_mfma_f32_16x16x32_bf16 v[76:79], v[144:147], v[210:213], 0
	v_mfma_f32_16x16x32_bf16 v[72:75], v[152:155], v[210:213], 0
	v_mfma_f32_16x16x32_bf16 v[124:127], v[148:151], v[180:183], v[124:127]
	v_mfma_f32_16x16x32_bf16 v[120:123], v[156:159], v[180:183], v[120:123]
	v_mfma_f32_16x16x32_bf16 v[108:111], v[148:151], v[198:201], v[108:111]
	v_mfma_f32_16x16x32_bf16 v[104:107], v[156:159], v[198:201], v[104:107]
	v_mfma_f32_16x16x32_bf16 v[92:95], v[148:151], v[206:209], v[92:95]
	v_mfma_f32_16x16x32_bf16 v[88:91], v[156:159], v[206:209], v[88:91]
	v_mfma_f32_16x16x32_bf16 v[76:79], v[148:151], v[214:217], v[76:79]
	v_mfma_f32_16x16x32_bf16 v[72:75], v[156:159], v[214:217], v[72:75]
	s_setprio 0
	s_setprio 1
	v_mfma_f32_16x16x32_bf16 v[116:119], v[160:163], v[176:179], 0
	v_mfma_f32_16x16x32_bf16 v[112:115], v[168:171], v[176:179], 0
	v_mfma_f32_16x16x32_bf16 v[100:103], v[160:163], v[194:197], 0
	v_mfma_f32_16x16x32_bf16 v[96:99], v[168:171], v[194:197], 0
	v_mfma_f32_16x16x32_bf16 v[84:87], v[160:163], v[202:205], 0
	v_mfma_f32_16x16x32_bf16 v[80:83], v[168:171], v[202:205], 0
	v_mfma_f32_16x16x32_bf16 v[68:71], v[160:163], v[210:213], 0
	v_mfma_f32_16x16x32_bf16 v[64:67], v[168:171], v[210:213], 0
	v_mfma_f32_16x16x32_bf16 v[116:119], v[164:167], v[180:183], v[116:119]
	v_mfma_f32_16x16x32_bf16 v[112:115], v[172:175], v[180:183], v[112:115]
	v_mfma_f32_16x16x32_bf16 v[100:103], v[164:167], v[198:201], v[100:103]
	v_mfma_f32_16x16x32_bf16 v[96:99], v[172:175], v[198:201], v[96:99]
	v_mfma_f32_16x16x32_bf16 v[84:87], v[164:167], v[206:209], v[84:87]
	v_mfma_f32_16x16x32_bf16 v[80:83], v[172:175], v[206:209], v[80:83]
	v_mfma_f32_16x16x32_bf16 v[68:71], v[164:167], v[214:217], v[68:71]
	v_mfma_f32_16x16x32_bf16 v[64:67], v[172:175], v[214:217], v[64:67]
	s_setprio 0
	s_barrier
	s_add_i32 s44, s63, s50
	v_lshl_add_u64 v[184:185], s[48:49], 0, v[130:131]
	s_mov_b32 m0, s44
	ds_read_b128 v[176:179], v191 offset:16384
	ds_read_b128 v[180:183], v191 offset:17408
	ds_read_b128 v[194:197], v191 offset:18432
	ds_read_b128 v[198:201], v191 offset:19456
	ds_read_b128 v[202:205], v191 offset:20480
	ds_read_b128 v[206:209], v191 offset:21504
	ds_read_b128 v[210:213], v191 offset:22528
	ds_read_b128 v[214:217], v191 offset:23552
	global_load_lds_dwordx4 v[184:185], off
	s_add_i32 m0, s44, 0x2000
	s_add_u32 s44, s48, 0x40000
	v_lshl_add_u64 v[218:219], s[48:49], 0, v[134:135]
	s_addc_u32 s45, s49, 0
	s_add_i32 s70, s64, s50
	global_load_lds_dwordx4 v[218:219], off
	v_lshl_add_u64 v[220:221], s[44:45], 0, v[130:131]
	s_mov_b32 m0, s70
	v_lshl_add_u64 v[222:223], s[74:75], 0, v[132:133]
	global_load_lds_dwordx4 v[220:221], off
	v_lshl_add_u64 v[220:221], s[44:45], 0, v[134:135]
	s_add_i32 m0, s70, 0x2000
	v_lshl_add_u64 v[224:225], v[222:223], 0, s[12:13]
	global_load_lds_dwordx4 v[220:221], off
	v_lshl_add_u64 v[220:221], s[74:75], 0, v[128:129]
	s_mov_b32 m0, s51
	s_nop 0
	global_load_lds_dwordx4 v[220:221], off
	s_mov_b32 m0, s52
	s_nop 0
	global_load_lds_dwordx4 v[224:225], off
	s_waitcnt vmcnt(8)
	s_waitcnt lgkmcnt(0)
	s_barrier
	s_setprio 1
	s_waitcnt lgkmcnt(0)
	v_mfma_f32_16x16x32_bf16 v[60:63], v[144:147], v[176:179], 0
	v_mfma_f32_16x16x32_bf16 v[56:59], v[152:155], v[176:179], 0
	v_mfma_f32_16x16x32_bf16 v[44:47], v[144:147], v[194:197], 0
	v_mfma_f32_16x16x32_bf16 v[40:43], v[152:155], v[194:197], 0
	v_mfma_f32_16x16x32_bf16 v[28:31], v[144:147], v[202:205], 0
	v_mfma_f32_16x16x32_bf16 v[24:27], v[152:155], v[202:205], 0
	v_mfma_f32_16x16x32_bf16 v[12:15], v[144:147], v[210:213], 0
	v_mfma_f32_16x16x32_bf16 v[8:11], v[152:155], v[210:213], 0
	v_mfma_f32_16x16x32_bf16 v[60:63], v[148:151], v[180:183], v[60:63]
	v_mfma_f32_16x16x32_bf16 v[56:59], v[156:159], v[180:183], v[56:59]
	v_mfma_f32_16x16x32_bf16 v[44:47], v[148:151], v[198:201], v[44:47]
	v_mfma_f32_16x16x32_bf16 v[40:43], v[156:159], v[198:201], v[40:43]
	v_mfma_f32_16x16x32_bf16 v[28:31], v[148:151], v[206:209], v[28:31]
	v_mfma_f32_16x16x32_bf16 v[24:27], v[156:159], v[206:209], v[24:27]
	v_mfma_f32_16x16x32_bf16 v[12:15], v[148:151], v[214:217], v[12:15]
	v_mfma_f32_16x16x32_bf16 v[8:11], v[156:159], v[214:217], v[8:11]
	s_setprio 0
	s_setprio 1
	v_mfma_f32_16x16x32_bf16 v[52:55], v[160:163], v[176:179], 0
	v_mfma_f32_16x16x32_bf16 v[48:51], v[168:171], v[176:179], 0
	v_mfma_f32_16x16x32_bf16 v[36:39], v[160:163], v[194:197], 0
	v_mfma_f32_16x16x32_bf16 v[32:35], v[168:171], v[194:197], 0
	v_mfma_f32_16x16x32_bf16 v[20:23], v[160:163], v[202:205], 0
	v_mfma_f32_16x16x32_bf16 v[16:19], v[168:171], v[202:205], 0
	v_mfma_f32_16x16x32_bf16 v[4:7], v[160:163], v[210:213], 0
	v_mfma_f32_16x16x32_bf16 v[0:3], v[168:171], v[210:213], 0
	v_mfma_f32_16x16x32_bf16 v[52:55], v[164:167], v[180:183], v[52:55]
	v_mfma_f32_16x16x32_bf16 v[48:51], v[172:175], v[180:183], v[48:51]
	v_mfma_f32_16x16x32_bf16 v[36:39], v[164:167], v[198:201], v[36:39]
	v_mfma_f32_16x16x32_bf16 v[32:35], v[172:175], v[198:201], v[32:35]
	v_mfma_f32_16x16x32_bf16 v[20:23], v[164:167], v[206:209], v[20:23]
	v_mfma_f32_16x16x32_bf16 v[16:19], v[172:175], v[206:209], v[16:19]
	v_mfma_f32_16x16x32_bf16 v[4:7], v[164:167], v[214:217], v[4:7]
	v_mfma_f32_16x16x32_bf16 v[0:3], v[172:175], v[214:217], v[0:3]
	s_setprio 0
	s_barrier
	s_add_i32 s44, 0, 0x18000
	s_add_i32 s70, 0, 0x1c000
	v_add_u32_e32 v156, s44, v187
	v_add_u32_e32 v172, s70, v187
	ds_read_b128 v[144:147], v156
	ds_read_b128 v[148:151], v156 offset:1024
	ds_read_b128 v[152:155], v156 offset:2048
	ds_read_b128 v[156:159], v156 offset:3072
	ds_read_b128 v[160:163], v172
	ds_read_b128 v[164:167], v172 offset:1024
	ds_read_b128 v[168:171], v172 offset:2048
	ds_read_b128 v[172:175], v172 offset:3072
	s_mov_b32 m0, s53
	v_lshl_add_u64 v[224:225], v[220:221], 0, s[10:11]
	ds_read_b128 v[176:179], v191 offset:32768
	ds_read_b128 v[180:183], v191 offset:33792
	ds_read_b128 v[194:197], v191 offset:34816
	ds_read_b128 v[198:201], v191 offset:35840
	ds_read_b128 v[202:205], v191 offset:36864
	ds_read_b128 v[206:209], v191 offset:37888
	ds_read_b128 v[210:213], v191 offset:38912
	ds_read_b128 v[214:217], v191 offset:39936
	global_load_lds_dwordx4 v[224:225], off
	v_lshl_add_u64 v[224:225], v[222:223], 0, s[14:15]
	s_mov_b32 m0, s54
	s_nop 0
	global_load_lds_dwordx4 v[224:225], off
	s_waitcnt vmcnt(8)
	s_waitcnt lgkmcnt(0)
	s_barrier
	s_setprio 1
	s_waitcnt lgkmcnt(0)
	v_mfma_f32_16x16x32_bf16 v[124:127], v[144:147], v[176:179], v[124:127]
	v_mfma_f32_16x16x32_bf16 v[120:123], v[152:155], v[176:179], v[120:123]
	v_mfma_f32_16x16x32_bf16 v[108:111], v[144:147], v[194:197], v[108:111]
	v_mfma_f32_16x16x32_bf16 v[104:107], v[152:155], v[194:197], v[104:107]
	v_mfma_f32_16x16x32_bf16 v[92:95], v[144:147], v[202:205], v[92:95]
	v_mfma_f32_16x16x32_bf16 v[88:91], v[152:155], v[202:205], v[88:91]
	v_mfma_f32_16x16x32_bf16 v[76:79], v[144:147], v[210:213], v[76:79]
	v_mfma_f32_16x16x32_bf16 v[72:75], v[152:155], v[210:213], v[72:75]
	v_mfma_f32_16x16x32_bf16 v[124:127], v[148:151], v[180:183], v[124:127]
	v_mfma_f32_16x16x32_bf16 v[120:123], v[156:159], v[180:183], v[120:123]
	v_mfma_f32_16x16x32_bf16 v[108:111], v[148:151], v[198:201], v[108:111]
	v_mfma_f32_16x16x32_bf16 v[104:107], v[156:159], v[198:201], v[104:107]
	v_mfma_f32_16x16x32_bf16 v[92:95], v[148:151], v[206:209], v[92:95]
	v_mfma_f32_16x16x32_bf16 v[88:91], v[156:159], v[206:209], v[88:91]
	v_mfma_f32_16x16x32_bf16 v[76:79], v[148:151], v[214:217], v[76:79]
	v_mfma_f32_16x16x32_bf16 v[72:75], v[156:159], v[214:217], v[72:75]
	s_setprio 0
	s_setprio 1
	v_mfma_f32_16x16x32_bf16 v[116:119], v[160:163], v[176:179], v[116:119]
	v_mfma_f32_16x16x32_bf16 v[112:115], v[168:171], v[176:179], v[112:115]
	v_mfma_f32_16x16x32_bf16 v[100:103], v[160:163], v[194:197], v[100:103]
	v_mfma_f32_16x16x32_bf16 v[96:99], v[168:171], v[194:197], v[96:99]
	v_mfma_f32_16x16x32_bf16 v[84:87], v[160:163], v[202:205], v[84:87]
	v_mfma_f32_16x16x32_bf16 v[80:83], v[168:171], v[202:205], v[80:83]
	v_mfma_f32_16x16x32_bf16 v[68:71], v[160:163], v[210:213], v[68:71]
	v_mfma_f32_16x16x32_bf16 v[64:67], v[168:171], v[210:213], v[64:67]
	v_mfma_f32_16x16x32_bf16 v[116:119], v[164:167], v[180:183], v[116:119]
	v_mfma_f32_16x16x32_bf16 v[112:115], v[172:175], v[180:183], v[112:115]
	v_mfma_f32_16x16x32_bf16 v[100:103], v[164:167], v[198:201], v[100:103]
	v_mfma_f32_16x16x32_bf16 v[96:99], v[172:175], v[198:201], v[96:99]
	v_mfma_f32_16x16x32_bf16 v[84:87], v[164:167], v[206:209], v[84:87]
	v_mfma_f32_16x16x32_bf16 v[80:83], v[172:175], v[206:209], v[80:83]
	v_mfma_f32_16x16x32_bf16 v[68:71], v[164:167], v[214:217], v[68:71]
	v_mfma_f32_16x16x32_bf16 v[64:67], v[172:175], v[214:217], v[64:67]
	s_setprio 0
	s_barrier
	s_add_i32 s44, s44, s50
	v_lshl_add_u64 v[184:185], v[184:185], 0, s[24:25]
	s_mov_b32 m0, s44
	ds_read_b128 v[176:179], v191 offset:49152
	ds_read_b128 v[180:183], v191 offset:50176
	ds_read_b128 v[194:197], v191 offset:51200
	ds_read_b128 v[198:201], v191 offset:52224
	ds_read_b128 v[202:205], v191 offset:53248
	ds_read_b128 v[206:209], v191 offset:54272
	ds_read_b128 v[210:213], v191 offset:55296
	ds_read_b128 v[214:217], v191 offset:56320
	global_load_lds_dwordx4 v[184:185], off
	s_add_i32 m0, s44, 0x2000
	s_add_u32 s44, s48, 0x40080
	v_lshl_add_u64 v[184:185], v[218:219], 0, s[24:25]
	s_addc_u32 s45, s49, 0
	s_add_i32 s48, s70, s50
	global_load_lds_dwordx4 v[184:185], off
	v_lshl_add_u64 v[184:185], s[44:45], 0, v[130:131]
	s_mov_b32 m0, s48
	s_nop 0
	global_load_lds_dwordx4 v[184:185], off
	v_lshl_add_u64 v[184:185], s[44:45], 0, v[134:135]
	s_add_i32 m0, s48, 0x2000
	s_nop 0
	global_load_lds_dwordx4 v[184:185], off
	v_lshl_add_u64 v[184:185], v[220:221], 0, s[24:25]
	s_mov_b32 m0, s58
	s_nop 0
	global_load_lds_dwordx4 v[184:185], off
	v_lshl_add_u64 v[184:185], v[222:223], 0, s[30:31]
	s_mov_b32 m0, s59
	s_nop 0
	global_load_lds_dwordx4 v[184:185], off
	s_waitcnt vmcnt(8)
	s_waitcnt lgkmcnt(0)
	s_barrier
	s_setprio 1
	s_waitcnt lgkmcnt(0)
	v_mfma_f32_16x16x32_bf16 v[60:63], v[144:147], v[176:179], v[60:63]
	v_mfma_f32_16x16x32_bf16 v[56:59], v[152:155], v[176:179], v[56:59]
	v_mfma_f32_16x16x32_bf16 v[44:47], v[144:147], v[194:197], v[44:47]
	v_mfma_f32_16x16x32_bf16 v[40:43], v[152:155], v[194:197], v[40:43]
	v_mfma_f32_16x16x32_bf16 v[28:31], v[144:147], v[202:205], v[28:31]
	v_mfma_f32_16x16x32_bf16 v[24:27], v[152:155], v[202:205], v[24:27]
	v_mfma_f32_16x16x32_bf16 v[12:15], v[144:147], v[210:213], v[12:15]
	v_mfma_f32_16x16x32_bf16 v[8:11], v[152:155], v[210:213], v[8:11]
	v_mfma_f32_16x16x32_bf16 v[60:63], v[148:151], v[180:183], v[60:63]
	v_mfma_f32_16x16x32_bf16 v[56:59], v[156:159], v[180:183], v[56:59]
	v_mfma_f32_16x16x32_bf16 v[44:47], v[148:151], v[198:201], v[44:47]
	v_mfma_f32_16x16x32_bf16 v[40:43], v[156:159], v[198:201], v[40:43]
	v_mfma_f32_16x16x32_bf16 v[28:31], v[148:151], v[206:209], v[28:31]
	v_mfma_f32_16x16x32_bf16 v[24:27], v[156:159], v[206:209], v[24:27]
	v_mfma_f32_16x16x32_bf16 v[12:15], v[148:151], v[214:217], v[12:15]
	v_mfma_f32_16x16x32_bf16 v[8:11], v[156:159], v[214:217], v[8:11]
	s_setprio 0
	s_setprio 1
	v_mfma_f32_16x16x32_bf16 v[52:55], v[160:163], v[176:179], v[52:55]
	v_mfma_f32_16x16x32_bf16 v[48:51], v[168:171], v[176:179], v[48:51]
	v_mfma_f32_16x16x32_bf16 v[36:39], v[160:163], v[194:197], v[36:39]
	v_mfma_f32_16x16x32_bf16 v[32:35], v[168:171], v[194:197], v[32:35]
	v_mfma_f32_16x16x32_bf16 v[20:23], v[160:163], v[202:205], v[20:23]
	v_mfma_f32_16x16x32_bf16 v[16:19], v[168:171], v[202:205], v[16:19]
	v_mfma_f32_16x16x32_bf16 v[4:7], v[160:163], v[210:213], v[4:7]
	v_mfma_f32_16x16x32_bf16 v[0:3], v[168:171], v[210:213], v[0:3]
	v_mfma_f32_16x16x32_bf16 v[52:55], v[164:167], v[180:183], v[52:55]
	v_mfma_f32_16x16x32_bf16 v[48:51], v[172:175], v[180:183], v[48:51]
	v_mfma_f32_16x16x32_bf16 v[36:39], v[164:167], v[198:201], v[36:39]
	v_mfma_f32_16x16x32_bf16 v[32:35], v[172:175], v[198:201], v[32:35]
	v_mfma_f32_16x16x32_bf16 v[20:23], v[164:167], v[206:209], v[20:23]
	v_mfma_f32_16x16x32_bf16 v[16:19], v[172:175], v[206:209], v[16:19]
	v_mfma_f32_16x16x32_bf16 v[4:7], v[164:167], v[214:217], v[4:7]
	v_mfma_f32_16x16x32_bf16 v[0:3], v[172:175], v[214:217], v[0:3]
	s_setprio 0
	s_barrier
	s_add_i32 s72, s72, 2
	s_add_u32 s69, s69, 0x100
	s_addc_u32 s71, s71, 0
	s_cmp_gt_u32 s72, 13
	s_mov_b64 s[44:45], s[46:47]
